# attnA: no K-frag prefetch, T0 unhoisted, later T3/R13-16; attnB: T3 partly early, barrier after P13; K-loop vmcnt(0) hoisted in QKV GEMMs
# speedup vs baseline: 1.0220x; 1.0071x over previous
; #define PG8_STAGE(bufoff, gbase, voff) do { _Pragma("unroll") for (int _i = 0; _i < 2; ++_i) \
;         __builtin_amdgcn_global_load_lds((const unsigned*)((const char*)(gbase) + (voff)[_i]), (PG8_LAS unsigned*)(lds + (bufoff) + ldsw + _i * 8192), 16, 0, 0); } while (0)
; #define PG8_LDA(dst, b, h) do { _Pragma("unroll") for (int m = 0; m < 4; ++m) _Pragma("unroll") for (int k = 0; k < 2; ++k) dst[m][k] = *(const PG8_LAS bf16x8*)(lds + PG8_SA(b, h) + aoff + m * 2048 + k * 1024); } while (0)
; #define PG8_LDB(dst, b, h) do { _Pragma("unroll") for (int n = 0; n < 2; ++n) _Pragma("unroll") for (int k = 0; k < 2; ++k) dst[n][k] = *(const PG8_LAS bf16x8*)(lds + PG8_SB(b, h) + boff + n * 2048 + k * 1024); } while (0)
; #define PG8_SCHED __builtin_amdgcn_sched_barrier(0)
; template <class Epi, class Sched, bool ALIGN_EPI = false, bool SP2 = false>
; __device__ __forceinline__ void gemm_phase(PG8_LAS unsigned char* lds, const Gemm g, const Sched& S, const Epi& E, const int tid) {
;     ...
;         const bool has_next = S.next(ui + 1, nxt);
;         const char* nA = has_next ? (const char*)g.A + (size_t)nxt.pm * tstep : cA; const char* nB = has_next ? (const char*)g.Bt + (size_t)nxt.pn * tstep : cB;
;         for (int t = 0; t < nt; t += 2) {
;             const bool last = (t == nt - 2);
;             const char* a1 = cA + (size_t)(t + 1) * kstep;
;             const char* a2 = last ? nA : cA + (size_t)(t + 2) * kstep; const char* b2 = last ? nB : cB + (size_t)(t + 2) * kstep;
;             const char* a3 = a2 + kstep; const char* b3 = b2 + kstep;
;             if (last && has_next) S.a_ready(nxt);
;             if constexpr (SP2) {
;             PG8_LDB(B0, 0, 0); PG8_LDB(B1, 0, 1); PG8_SCHED; PG8_LDA(At, 0, 0); PG8_STAGE(PG8_SA(1, 1), a1 + hstep, voffA);
;     ...
;         if constexpr (!Epi::ACC_INIT) {
; #pragma unroll
;         for (int a = 0; a < 2; ++a)
; #pragma unroll
;             for (int b = 0; b < 2; ++b)
; #pragma unroll
;                 for (int m = 0; m < 4; ++m)
; #pragma unroll
;                     for (int n = 0; n < 2; ++n) acc[a][b][m][n] = (f32x4){0.f, 0.f, 0.f, 0.f};
;         }
;         cur = nxt; cA = nA; cB = nB; ++ui;
.LBB0_318:
	s_ashr_i32 s29, s28, 31
	s_lshl_b64 s[30:31], s[28:29], 20
	s_add_u32 s30, s48, s30
	s_addc_u32 s31, s49, s31
	s_and_b64 s[34:35], s[6:7], exec
	s_cselect_b32 s9, s31, s43
	s_cselect_b32 s29, s30, s42
	s_ashr_i32 s27, s26, 31
	s_lshl_b64 s[34:35], s[26:27], 20
	s_add_u32 s34, s50, s34
	s_addc_u32 s35, s51, s35
	s_and_b64 s[46:47], s[6:7], exec
	s_cselect_b32 s27, s35, s45
	s_cselect_b32 s37, s34, s44
	s_add_u32 s42, s42, 0x80080
	s_addc_u32 s43, s43, 0
	s_add_u32 s69, s44, 0x100
	v_mov_b32_e32 v0, 0
	s_addc_u32 s92, s45, 0
	s_mov_b32 s76, -2
	v_mov_b32_e32 v1, v0
	v_mov_b32_e32 v2, v0
	v_mov_b32_e32 v3, v0
	v_mov_b32_e32 v4, v0
	v_mov_b32_e32 v5, v0
	v_mov_b32_e32 v6, v0
	v_mov_b32_e32 v7, v0
	v_mov_b32_e32 v16, v0
	v_mov_b32_e32 v17, v0
	v_mov_b32_e32 v18, v0
	v_mov_b32_e32 v19, v0
	v_mov_b32_e32 v20, v0
	v_mov_b32_e32 v21, v0
	v_mov_b32_e32 v22, v0
	v_mov_b32_e32 v23, v0
	v_mov_b32_e32 v32, v0
	v_mov_b32_e32 v33, v0
	v_mov_b32_e32 v34, v0
	v_mov_b32_e32 v35, v0
	v_mov_b32_e32 v36, v0
	v_mov_b32_e32 v37, v0
	v_mov_b32_e32 v38, v0
	v_mov_b32_e32 v39, v0
	v_mov_b32_e32 v48, v0
	v_mov_b32_e32 v49, v0
	v_mov_b32_e32 v50, v0
	v_mov_b32_e32 v51, v0
	v_mov_b32_e32 v52, v0
	v_mov_b32_e32 v53, v0
	v_mov_b32_e32 v54, v0
	v_mov_b32_e32 v55, v0
	v_mov_b32_e32 v8, v0
	v_mov_b32_e32 v9, v0
	v_mov_b32_e32 v10, v0
	v_mov_b32_e32 v11, v0
	v_mov_b32_e32 v12, v0
	v_mov_b32_e32 v13, v0
	v_mov_b32_e32 v14, v0
	v_mov_b32_e32 v15, v0
	v_mov_b32_e32 v24, v0
	v_mov_b32_e32 v25, v0
	v_mov_b32_e32 v26, v0
	v_mov_b32_e32 v27, v0
	v_mov_b32_e32 v28, v0
	v_mov_b32_e32 v29, v0
	v_mov_b32_e32 v30, v0
	v_mov_b32_e32 v31, v0
	v_mov_b32_e32 v40, v0
	v_mov_b32_e32 v41, v0
	v_mov_b32_e32 v42, v0
	v_mov_b32_e32 v43, v0
	v_mov_b32_e32 v44, v0
	v_mov_b32_e32 v45, v0
	v_mov_b32_e32 v46, v0
	v_mov_b32_e32 v47, v0
	v_mov_b32_e32 v56, v0
	v_mov_b32_e32 v57, v0
	v_mov_b32_e32 v58, v0
	v_mov_b32_e32 v59, v0
	v_mov_b32_e32 v60, v0
	v_mov_b32_e32 v61, v0
	v_mov_b32_e32 v62, v0
	v_mov_b32_e32 v63, v0
	v_mov_b32_e32 v64, v0
	v_mov_b32_e32 v65, v0
	v_mov_b32_e32 v66, v0
	v_mov_b32_e32 v67, v0
	v_mov_b32_e32 v68, v0
	v_mov_b32_e32 v69, v0
	v_mov_b32_e32 v70, v0
	v_mov_b32_e32 v71, v0
	v_mov_b32_e32 v80, v0
	v_mov_b32_e32 v81, v0
	v_mov_b32_e32 v82, v0
	v_mov_b32_e32 v83, v0
	v_mov_b32_e32 v84, v0
	v_mov_b32_e32 v85, v0
	v_mov_b32_e32 v86, v0
	v_mov_b32_e32 v87, v0
	v_mov_b32_e32 v96, v0
	v_mov_b32_e32 v97, v0
	v_mov_b32_e32 v98, v0
	v_mov_b32_e32 v99, v0
	v_mov_b32_e32 v100, v0
	v_mov_b32_e32 v101, v0
	v_mov_b32_e32 v102, v0
	v_mov_b32_e32 v103, v0
	v_mov_b32_e32 v112, v0
	v_mov_b32_e32 v113, v0
	v_mov_b32_e32 v114, v0
	v_mov_b32_e32 v115, v0
	v_mov_b32_e32 v116, v0
	v_mov_b32_e32 v117, v0
	v_mov_b32_e32 v118, v0
	v_mov_b32_e32 v119, v0
	v_mov_b32_e32 v72, v0
	v_mov_b32_e32 v73, v0
	v_mov_b32_e32 v74, v0
	v_mov_b32_e32 v75, v0
	v_mov_b32_e32 v76, v0
	v_mov_b32_e32 v77, v0
	v_mov_b32_e32 v78, v0
	v_mov_b32_e32 v79, v0
	v_mov_b32_e32 v88, v0
	v_mov_b32_e32 v89, v0
	v_mov_b32_e32 v90, v0
	v_mov_b32_e32 v91, v0
	v_mov_b32_e32 v92, v0
	v_mov_b32_e32 v93, v0
	v_mov_b32_e32 v94, v0
	v_mov_b32_e32 v95, v0
	v_mov_b32_e32 v104, v0
	v_mov_b32_e32 v105, v0
	v_mov_b32_e32 v106, v0
	v_mov_b32_e32 v107, v0
	v_mov_b32_e32 v108, v0
	v_mov_b32_e32 v109, v0
	v_mov_b32_e32 v110, v0
	v_mov_b32_e32 v111, v0
	v_mov_b32_e32 v120, v0
	v_mov_b32_e32 v121, v0
	v_mov_b32_e32 v122, v0
	v_mov_b32_e32 v123, v0
	v_mov_b32_e32 v124, v0
	v_mov_b32_e32 v125, v0
	v_mov_b32_e32 v126, v0
	v_mov_b32_e32 v127, v0
	s_waitcnt vmcnt(0)
.LBB0_319:
	s_add_u32 s44, s42, 0xfff80080
	s_addc_u32 s45, s43, -1
	s_add_i32 s77, 0, 0x10000
	s_cmp_eq_u32 s76, 28
	s_cselect_b32 s47, s9, s45
	s_cselect_b32 s46, s29, s44
	v_add_u32_e32 v136, s77, v178
	s_cselect_b32 s45, s27, s92
	s_cselect_b32 s44, s37, s69
	s_add_i32 s80, 0, 0x14000
	ds_read_b128 v[128:131], v136
	ds_read_b128 v[132:135], v136 offset:1024
	ds_read_b128 v[150:153], v136 offset:2048
	ds_read_b128 v[154:157], v136 offset:3072
	v_add_u32_e32 v136, s80, v178
	ds_read_b128 v[158:161], v136
	ds_read_b128 v[162:165], v136 offset:1024
	ds_read_b128 v[166:169], v136 offset:2048
	ds_read_b128 v[170:173], v136 offset:3072
	v_lshl_add_u64 v[136:137], s[42:43], 0, v[146:147]
	s_add_i32 m0, s53, 0xc000
	ds_read_b128 v[174:177], v179
	ds_read_b128 v[180:183], v179 offset:1024
	ds_read_b128 v[184:187], v179 offset:2048
	ds_read_b128 v[188:191], v179 offset:3072
	ds_read_b128 v[192:195], v179 offset:4096
	ds_read_b128 v[196:199], v179 offset:5120
	ds_read_b128 v[200:203], v179 offset:6144
	ds_read_b128 v[206:209], v179 offset:7168
	global_load_lds_dwordx4 v[136:137], off
	v_lshl_add_u64 v[136:137], s[42:43], 0, v[148:149]
	s_add_i32 m0, s53, 0xe000
	s_nop 0
	global_load_lds_dwordx4 v[136:137], off
	s_waitcnt vmcnt(8)
	s_waitcnt lgkmcnt(0)
	s_barrier
; #define PG8_STAGE(bufoff, gbase, voff) do { _Pragma("unroll") for (int _i = 0; _i < 2; ++_i) \
;         __builtin_amdgcn_global_load_lds((const unsigned*)((const char*)(gbase) + (voff)[_i]), (PG8_LAS unsigned*)(lds + (bufoff) + ldsw + _i * 8192), 16, 0, 0); } while (0)
; #define PG8_LDA(dst, b, h) do { _Pragma("unroll") for (int m = 0; m < 4; ++m) _Pragma("unroll") for (int k = 0; k < 2; ++k) dst[m][k] = *(const PG8_LAS bf16x8*)(lds + PG8_SA(b, h) + aoff + m * 2048 + k * 1024); } while (0)
; #define PG8_LDB(dst, b, h) do { _Pragma("unroll") for (int n = 0; n < 2; ++n) _Pragma("unroll") for (int k = 0; k < 2; ++k) dst[n][k] = *(const PG8_LAS bf16x8*)(lds + PG8_SB(b, h) + boff + n * 2048 + k * 1024); } while (0)
; #define PG8_MMA(ai, bj, At, Bt) do { __builtin_amdgcn_s_setprio(1); _Pragma("unroll") for (int m = 0; m < 4; ++m) _Pragma("unroll") for (int n = 0; n < 2; ++n) _Pragma("unroll") for (int k = 0; k < 2; ++k) \
;         acc[ai][bj][m][n] = __builtin_amdgcn_mfma_f32_16x16x32_bf16(Bt[n][k], At[m][k], acc[ai][bj][m][n], 0, 0, 0); __builtin_amdgcn_s_setprio(0); } while (0)
; #define PG8_WAIT_V(n) asm volatile("s_waitcnt vmcnt(" #n ")" ::: "memory")
; #define PG8_WAIT_L(n) asm volatile("s_waitcnt lgkmcnt(" #n ")" ::: "memory")
; #define PG8_BAR __builtin_amdgcn_s_barrier()
; #define PG8_SCHED __builtin_amdgcn_sched_barrier(0)
; template <class Epi, class Sched, bool ALIGN_EPI = false, bool SP2 = false>
; __device__ __forceinline__ void gemm_phase(PG8_LAS unsigned char* lds, const Gemm g, const Sched& S, const Epi& E, const int tid) {
;     ...
;             PG8_LDB(B0, 0, 0); PG8_LDB(B1, 0, 1); PG8_SCHED; PG8_LDA(At, 0, 0); PG8_STAGE(PG8_SA(1, 1), a1 + hstep, voffA);
;             PG8_WAIT_V(8); PG8_WAIT_L(0); PG8_BAR; PG8_MMA(0, 0, At, B0); PG8_MMA(0, 1, At, B1); PG8_BAR; PG8_SCHED;
;             PG8_LDA(At, 0, 1); PG8_STAGE(PG8_SB(0, 0), b2, voffB); PG8_STAGE(PG8_SB(0, 1), b2 + hstep, voffB); PG8_STAGE(PG8_SA(0, 0), a2, voffA);
;             PG8_WAIT_V(8); PG8_WAIT_L(0); PG8_BAR; PG8_MMA(1, 0, At, B0); PG8_MMA(1, 1, At, B1); PG8_BAR; PG8_SCHED;
	s_setprio 1
	s_waitcnt lgkmcnt(0)
	v_mfma_f32_16x16x32_bf16 v[124:127], v[128:131], v[174:177], v[124:127]
	v_mfma_f32_16x16x32_bf16 v[120:123], v[150:153], v[174:177], v[120:123]
	v_mfma_f32_16x16x32_bf16 v[108:111], v[128:131], v[184:187], v[108:111]
	v_mfma_f32_16x16x32_bf16 v[104:107], v[150:153], v[184:187], v[104:107]
	v_mfma_f32_16x16x32_bf16 v[92:95], v[128:131], v[192:195], v[92:95]
	v_mfma_f32_16x16x32_bf16 v[88:91], v[150:153], v[192:195], v[88:91]
	v_mfma_f32_16x16x32_bf16 v[76:79], v[128:131], v[200:203], v[76:79]
	v_mfma_f32_16x16x32_bf16 v[72:75], v[150:153], v[200:203], v[72:75]
	v_mfma_f32_16x16x32_bf16 v[124:127], v[132:135], v[180:183], v[124:127]
	v_mfma_f32_16x16x32_bf16 v[120:123], v[154:157], v[180:183], v[120:123]
	v_mfma_f32_16x16x32_bf16 v[108:111], v[132:135], v[188:191], v[108:111]
	v_mfma_f32_16x16x32_bf16 v[104:107], v[154:157], v[188:191], v[104:107]
	v_mfma_f32_16x16x32_bf16 v[92:95], v[132:135], v[196:199], v[92:95]
	v_mfma_f32_16x16x32_bf16 v[88:91], v[154:157], v[196:199], v[88:91]
	v_mfma_f32_16x16x32_bf16 v[76:79], v[132:135], v[206:209], v[76:79]
	v_mfma_f32_16x16x32_bf16 v[72:75], v[154:157], v[206:209], v[72:75]
	s_setprio 0
	s_setprio 1
	v_mfma_f32_16x16x32_bf16 v[116:119], v[158:161], v[174:177], v[116:119]
	v_mfma_f32_16x16x32_bf16 v[112:115], v[166:169], v[174:177], v[112:115]
	v_mfma_f32_16x16x32_bf16 v[100:103], v[158:161], v[184:187], v[100:103]
	v_mfma_f32_16x16x32_bf16 v[96:99], v[166:169], v[184:187], v[96:99]
	v_mfma_f32_16x16x32_bf16 v[84:87], v[158:161], v[192:195], v[84:87]
	v_mfma_f32_16x16x32_bf16 v[80:83], v[166:169], v[192:195], v[80:83]
	v_mfma_f32_16x16x32_bf16 v[68:71], v[158:161], v[200:203], v[68:71]
	v_mfma_f32_16x16x32_bf16 v[64:67], v[166:169], v[200:203], v[64:67]
	v_mfma_f32_16x16x32_bf16 v[116:119], v[162:165], v[180:183], v[116:119]
	v_mfma_f32_16x16x32_bf16 v[112:115], v[170:173], v[180:183], v[112:115]
	v_mfma_f32_16x16x32_bf16 v[100:103], v[162:165], v[188:191], v[100:103]
	v_mfma_f32_16x16x32_bf16 v[96:99], v[170:173], v[188:191], v[96:99]
	v_mfma_f32_16x16x32_bf16 v[84:87], v[162:165], v[196:199], v[84:87]
	v_mfma_f32_16x16x32_bf16 v[80:83], v[170:173], v[196:199], v[80:83]
	v_mfma_f32_16x16x32_bf16 v[68:71], v[162:165], v[206:209], v[68:71]
	v_mfma_f32_16x16x32_bf16 v[64:67], v[170:173], v[206:209], v[64:67]
	s_setprio 0
	s_barrier
	s_add_i32 s77, s77, s52
	v_lshl_add_u64 v[136:137], s[44:45], 0, v[140:141]
	s_mov_b32 m0, s77
	ds_read_b128 v[174:177], v179 offset:16384
	ds_read_b128 v[180:183], v179 offset:17408
	ds_read_b128 v[184:187], v179 offset:18432
	ds_read_b128 v[188:191], v179 offset:19456
	ds_read_b128 v[192:195], v179 offset:20480
	ds_read_b128 v[196:199], v179 offset:21504
	ds_read_b128 v[200:203], v179 offset:22528
	ds_read_b128 v[206:209], v179 offset:23552
	global_load_lds_dwordx4 v[136:137], off
	s_add_i32 m0, s77, 0x2000
	s_add_u32 s78, s44, 0x80000
	v_lshl_add_u64 v[210:211], s[44:45], 0, v[144:145]
	s_addc_u32 s79, s45, 0
	s_add_i32 s77, s80, s52
	global_load_lds_dwordx4 v[210:211], off
	v_lshl_add_u64 v[212:213], s[78:79], 0, v[140:141]
	s_mov_b32 m0, s77
	v_lshl_add_u64 v[214:215], s[46:47], 0, v[142:143]
	global_load_lds_dwordx4 v[212:213], off
	v_lshl_add_u64 v[212:213], s[78:79], 0, v[144:145]
	s_add_i32 m0, s77, 0x2000
	s_nop 0
	global_load_lds_dwordx4 v[212:213], off
	v_lshl_add_u64 v[212:213], s[46:47], 0, v[138:139]
	s_mov_b32 m0, s53
	s_nop 0
	global_load_lds_dwordx4 v[212:213], off
	s_mov_b32 m0, s54
	s_nop 0
	global_load_lds_dwordx4 v[214:215], off
	s_waitcnt vmcnt(8)
	s_waitcnt lgkmcnt(0)
	s_barrier
	s_setprio 1
	s_waitcnt lgkmcnt(0)
	v_mfma_f32_16x16x32_bf16 v[60:63], v[128:131], v[174:177], v[60:63]
	v_mfma_f32_16x16x32_bf16 v[56:59], v[150:153], v[174:177], v[56:59]
	v_mfma_f32_16x16x32_bf16 v[44:47], v[128:131], v[184:187], v[44:47]
	v_mfma_f32_16x16x32_bf16 v[40:43], v[150:153], v[184:187], v[40:43]
	v_mfma_f32_16x16x32_bf16 v[28:31], v[128:131], v[192:195], v[28:31]
	v_mfma_f32_16x16x32_bf16 v[24:27], v[150:153], v[192:195], v[24:27]
	v_mfma_f32_16x16x32_bf16 v[12:15], v[128:131], v[200:203], v[12:15]
	v_mfma_f32_16x16x32_bf16 v[8:11], v[150:153], v[200:203], v[8:11]
	v_mfma_f32_16x16x32_bf16 v[60:63], v[132:135], v[180:183], v[60:63]
	v_mfma_f32_16x16x32_bf16 v[56:59], v[154:157], v[180:183], v[56:59]
	v_mfma_f32_16x16x32_bf16 v[44:47], v[132:135], v[188:191], v[44:47]
	v_mfma_f32_16x16x32_bf16 v[40:43], v[154:157], v[188:191], v[40:43]
	v_mfma_f32_16x16x32_bf16 v[28:31], v[132:135], v[196:199], v[28:31]
	v_mfma_f32_16x16x32_bf16 v[24:27], v[154:157], v[196:199], v[24:27]
	v_mfma_f32_16x16x32_bf16 v[12:15], v[132:135], v[206:209], v[12:15]
	v_mfma_f32_16x16x32_bf16 v[8:11], v[154:157], v[206:209], v[8:11]
	s_setprio 0
	s_setprio 1
	v_mfma_f32_16x16x32_bf16 v[52:55], v[158:161], v[174:177], v[52:55]
	v_mfma_f32_16x16x32_bf16 v[48:51], v[166:169], v[174:177], v[48:51]
	v_mfma_f32_16x16x32_bf16 v[36:39], v[158:161], v[184:187], v[36:39]
	v_mfma_f32_16x16x32_bf16 v[32:35], v[166:169], v[184:187], v[32:35]
	v_mfma_f32_16x16x32_bf16 v[20:23], v[158:161], v[192:195], v[20:23]
	v_mfma_f32_16x16x32_bf16 v[16:19], v[166:169], v[192:195], v[16:19]
	v_mfma_f32_16x16x32_bf16 v[4:7], v[158:161], v[200:203], v[4:7]
	v_mfma_f32_16x16x32_bf16 v[0:3], v[166:169], v[200:203], v[0:3]
	v_mfma_f32_16x16x32_bf16 v[52:55], v[162:165], v[180:183], v[52:55]
	v_mfma_f32_16x16x32_bf16 v[48:51], v[170:173], v[180:183], v[48:51]
	v_mfma_f32_16x16x32_bf16 v[36:39], v[162:165], v[188:191], v[36:39]
	v_mfma_f32_16x16x32_bf16 v[32:35], v[170:173], v[188:191], v[32:35]
	v_mfma_f32_16x16x32_bf16 v[20:23], v[162:165], v[196:199], v[20:23]
	v_mfma_f32_16x16x32_bf16 v[16:19], v[170:173], v[196:199], v[16:19]
	v_mfma_f32_16x16x32_bf16 v[4:7], v[162:165], v[206:209], v[4:7]
	v_mfma_f32_16x16x32_bf16 v[0:3], v[170:173], v[206:209], v[0:3]
	s_setprio 0
	s_barrier
; #define PG8_STAGE(bufoff, gbase, voff) do { _Pragma("unroll") for (int _i = 0; _i < 2; ++_i) \
;         __builtin_amdgcn_global_load_lds((const unsigned*)((const char*)(gbase) + (voff)[_i]), (PG8_LAS unsigned*)(lds + (bufoff) + ldsw + _i * 8192), 16, 0, 0); } while (0)
; #define PG8_LDA(dst, b, h) do { _Pragma("unroll") for (int m = 0; m < 4; ++m) _Pragma("unroll") for (int k = 0; k < 2; ++k) dst[m][k] = *(const PG8_LAS bf16x8*)(lds + PG8_SA(b, h) + aoff + m * 2048 + k * 1024); } while (0)
; #define PG8_LDB(dst, b, h) do { _Pragma("unroll") for (int n = 0; n < 2; ++n) _Pragma("unroll") for (int k = 0; k < 2; ++k) dst[n][k] = *(const PG8_LAS bf16x8*)(lds + PG8_SB(b, h) + boff + n * 2048 + k * 1024); } while (0)
; #define PG8_MMA(ai, bj, At, Bt) do { __builtin_amdgcn_s_setprio(1); _Pragma("unroll") for (int m = 0; m < 4; ++m) _Pragma("unroll") for (int n = 0; n < 2; ++n) _Pragma("unroll") for (int k = 0; k < 2; ++k) \
;         acc[ai][bj][m][n] = __builtin_amdgcn_mfma_f32_16x16x32_bf16(Bt[n][k], At[m][k], acc[ai][bj][m][n], 0, 0, 0); __builtin_amdgcn_s_setprio(0); } while (0)
; #define PG8_WAIT_V(n) asm volatile("s_waitcnt vmcnt(" #n ")" ::: "memory")
; #define PG8_WAIT_L(n) asm volatile("s_waitcnt lgkmcnt(" #n ")" ::: "memory")
; #define PG8_BAR __builtin_amdgcn_s_barrier()
; #define PG8_SCHED __builtin_amdgcn_sched_barrier(0)
; template <class Epi, class Sched, bool ALIGN_EPI = false, bool SP2 = false>
; __device__ __forceinline__ void gemm_phase(PG8_LAS unsigned char* lds, const Gemm g, const Sched& S, const Epi& E, const int tid) {
;     ...
;             PG8_LDB(B0, 1, 0); PG8_LDB(B1, 1, 1); PG8_SCHED; PG8_LDA(At, 1, 0); PG8_STAGE(PG8_SA(0, 1), a2 + hstep, voffA);
;             PG8_WAIT_V(8); PG8_WAIT_L(0); PG8_BAR; PG8_MMA(0, 0, At, B0); PG8_MMA(0, 1, At, B1); PG8_BAR; PG8_SCHED;
	s_add_i32 s77, 0, 0x18000
	s_add_i32 s78, 0, 0x1c000
	v_add_u32_e32 v154, s77, v178
	v_add_u32_e32 v170, s78, v178
	ds_read_b128 v[128:131], v154
	ds_read_b128 v[132:135], v154 offset:1024
	ds_read_b128 v[150:153], v154 offset:2048
	ds_read_b128 v[154:157], v154 offset:3072
	ds_read_b128 v[158:161], v170
	ds_read_b128 v[162:165], v170 offset:1024
	ds_read_b128 v[166:169], v170 offset:2048
	ds_read_b128 v[170:173], v170 offset:3072
	s_add_u32 s46, s46, 0x80000
	s_addc_u32 s47, s47, 0
	s_mov_b32 m0, s55
	v_lshl_add_u64 v[216:217], s[46:47], 0, v[138:139]
	ds_read_b128 v[174:177], v179 offset:32768
	ds_read_b128 v[180:183], v179 offset:33792
	ds_read_b128 v[184:187], v179 offset:34816
	ds_read_b128 v[188:191], v179 offset:35840
	ds_read_b128 v[192:195], v179 offset:36864
	ds_read_b128 v[196:199], v179 offset:37888
	ds_read_b128 v[200:203], v179 offset:38912
	ds_read_b128 v[206:209], v179 offset:39936
	global_load_lds_dwordx4 v[216:217], off
	v_lshl_add_u64 v[216:217], s[46:47], 0, v[142:143]
	s_mov_b32 m0, s0
	s_nop 0
	global_load_lds_dwordx4 v[216:217], off
	s_waitcnt vmcnt(8)
	s_waitcnt lgkmcnt(0)
	s_barrier
	s_setprio 1
	s_waitcnt lgkmcnt(0)
	v_mfma_f32_16x16x32_bf16 v[124:127], v[128:131], v[174:177], v[124:127]
	v_mfma_f32_16x16x32_bf16 v[120:123], v[150:153], v[174:177], v[120:123]
	v_mfma_f32_16x16x32_bf16 v[108:111], v[128:131], v[184:187], v[108:111]
	v_mfma_f32_16x16x32_bf16 v[104:107], v[150:153], v[184:187], v[104:107]
	v_mfma_f32_16x16x32_bf16 v[92:95], v[128:131], v[192:195], v[92:95]
	v_mfma_f32_16x16x32_bf16 v[88:91], v[150:153], v[192:195], v[88:91]
	v_mfma_f32_16x16x32_bf16 v[76:79], v[128:131], v[200:203], v[76:79]
	v_mfma_f32_16x16x32_bf16 v[72:75], v[150:153], v[200:203], v[72:75]
	v_mfma_f32_16x16x32_bf16 v[124:127], v[132:135], v[180:183], v[124:127]
	v_mfma_f32_16x16x32_bf16 v[120:123], v[154:157], v[180:183], v[120:123]
	v_mfma_f32_16x16x32_bf16 v[108:111], v[132:135], v[188:191], v[108:111]
	v_mfma_f32_16x16x32_bf16 v[104:107], v[154:157], v[188:191], v[104:107]
	v_mfma_f32_16x16x32_bf16 v[92:95], v[132:135], v[196:199], v[92:95]
	v_mfma_f32_16x16x32_bf16 v[88:91], v[154:157], v[196:199], v[88:91]
	v_mfma_f32_16x16x32_bf16 v[76:79], v[132:135], v[206:209], v[76:79]
	v_mfma_f32_16x16x32_bf16 v[72:75], v[154:157], v[206:209], v[72:75]
	s_setprio 0
	s_setprio 1
	v_mfma_f32_16x16x32_bf16 v[116:119], v[158:161], v[174:177], v[116:119]
	v_mfma_f32_16x16x32_bf16 v[112:115], v[166:169], v[174:177], v[112:115]
	v_mfma_f32_16x16x32_bf16 v[100:103], v[158:161], v[184:187], v[100:103]
	v_mfma_f32_16x16x32_bf16 v[96:99], v[166:169], v[184:187], v[96:99]
	v_mfma_f32_16x16x32_bf16 v[84:87], v[158:161], v[192:195], v[84:87]
	v_mfma_f32_16x16x32_bf16 v[80:83], v[166:169], v[192:195], v[80:83]
	v_mfma_f32_16x16x32_bf16 v[68:71], v[158:161], v[200:203], v[68:71]
	v_mfma_f32_16x16x32_bf16 v[64:67], v[166:169], v[200:203], v[64:67]
	v_mfma_f32_16x16x32_bf16 v[116:119], v[162:165], v[180:183], v[116:119]
	v_mfma_f32_16x16x32_bf16 v[112:115], v[170:173], v[180:183], v[112:115]
	v_mfma_f32_16x16x32_bf16 v[100:103], v[162:165], v[188:191], v[100:103]
	v_mfma_f32_16x16x32_bf16 v[96:99], v[170:173], v[188:191], v[96:99]
	v_mfma_f32_16x16x32_bf16 v[84:87], v[162:165], v[196:199], v[84:87]
	v_mfma_f32_16x16x32_bf16 v[80:83], v[170:173], v[196:199], v[80:83]
	v_mfma_f32_16x16x32_bf16 v[68:71], v[162:165], v[206:209], v[68:71]
	v_mfma_f32_16x16x32_bf16 v[64:67], v[170:173], v[206:209], v[64:67]
	s_setprio 0
	s_barrier
; #define PG8_STAGE(bufoff, gbase, voff) do { _Pragma("unroll") for (int _i = 0; _i < 2; ++_i) \
;         __builtin_amdgcn_global_load_lds((const unsigned*)((const char*)(gbase) + (voff)[_i]), (PG8_LAS unsigned*)(lds + (bufoff) + ldsw + _i * 8192), 16, 0, 0); } while (0)
; #define PG8_LDA(dst, b, h) do { _Pragma("unroll") for (int m = 0; m < 4; ++m) _Pragma("unroll") for (int k = 0; k < 2; ++k) dst[m][k] = *(const PG8_LAS bf16x8*)(lds + PG8_SA(b, h) + aoff + m * 2048 + k * 1024); } while (0)
; #define PG8_MMA(ai, bj, At, Bt) do { __builtin_amdgcn_s_setprio(1); _Pragma("unroll") for (int m = 0; m < 4; ++m) _Pragma("unroll") for (int n = 0; n < 2; ++n) _Pragma("unroll") for (int k = 0; k < 2; ++k) \
;         acc[ai][bj][m][n] = __builtin_amdgcn_mfma_f32_16x16x32_bf16(Bt[n][k], At[m][k], acc[ai][bj][m][n], 0, 0, 0); __builtin_amdgcn_s_setprio(0); } while (0)
; #define PG8_WAIT_V(n) asm volatile("s_waitcnt vmcnt(" #n ")" ::: "memory")
; #define PG8_WAIT_L(n) asm volatile("s_waitcnt lgkmcnt(" #n ")" ::: "memory")
; #define PG8_BAR __builtin_amdgcn_s_barrier()
; #define PG8_SCHED __builtin_amdgcn_sched_barrier(0)
; template <class Epi, class Sched, bool ALIGN_EPI = false, bool SP2 = false>
; __device__ __forceinline__ void gemm_phase(PG8_LAS unsigned char* lds, const Gemm g, const Sched& S, const Epi& E, const int tid) {
;     ...
;         for (int t = 0; t < nt; t += 2) {
;     ...
;             PG8_LDA(At, 1, 1); PG8_STAGE(PG8_SB(1, 0), b3, voffB); PG8_STAGE(PG8_SB(1, 1), b3 + hstep, voffB); PG8_STAGE(PG8_SA(1, 0), a3, voffA);
;             PG8_WAIT_V(8); PG8_WAIT_L(0); PG8_BAR; PG8_MMA(1, 0, At, B0); PG8_MMA(1, 1, At, B1); PG8_BAR; PG8_SCHED;
	s_add_i32 s46, s77, s52
	v_lshl_add_u64 v[136:137], v[136:137], 0, s[70:71]
	s_mov_b32 m0, s46
	ds_read_b128 v[174:177], v179 offset:49152
	ds_read_b128 v[180:183], v179 offset:50176
	ds_read_b128 v[184:187], v179 offset:51200
	ds_read_b128 v[188:191], v179 offset:52224
	ds_read_b128 v[192:195], v179 offset:53248
	ds_read_b128 v[196:199], v179 offset:54272
	ds_read_b128 v[200:203], v179 offset:55296
	ds_read_b128 v[206:209], v179 offset:56320
	global_load_lds_dwordx4 v[136:137], off
	s_add_i32 m0, s46, 0x2000
	s_add_u32 s44, s44, 0x80080
	v_lshl_add_u64 v[136:137], v[210:211], 0, s[70:71]
	s_addc_u32 s45, s45, 0
	s_add_i32 s46, s78, s52
	global_load_lds_dwordx4 v[136:137], off
	v_lshl_add_u64 v[136:137], s[44:45], 0, v[140:141]
	s_mov_b32 m0, s46
	s_nop 0
	global_load_lds_dwordx4 v[136:137], off
	v_lshl_add_u64 v[136:137], s[44:45], 0, v[144:145]
	s_add_i32 m0, s46, 0x2000
	s_nop 0
	global_load_lds_dwordx4 v[136:137], off
	v_lshl_add_u64 v[136:137], v[212:213], 0, s[70:71]
	s_mov_b32 m0, s11
	s_nop 0
	global_load_lds_dwordx4 v[136:137], off
	v_lshl_add_u64 v[136:137], v[214:215], 0, s[70:71]
	s_mov_b32 m0, s64
	s_nop 0
	global_load_lds_dwordx4 v[136:137], off
	s_waitcnt vmcnt(8)
	s_waitcnt lgkmcnt(0)
	s_barrier
	s_setprio 1
	s_waitcnt lgkmcnt(0)
	v_mfma_f32_16x16x32_bf16 v[60:63], v[128:131], v[174:177], v[60:63]
	v_mfma_f32_16x16x32_bf16 v[56:59], v[150:153], v[174:177], v[56:59]
	v_mfma_f32_16x16x32_bf16 v[44:47], v[128:131], v[184:187], v[44:47]
	v_mfma_f32_16x16x32_bf16 v[40:43], v[150:153], v[184:187], v[40:43]
	v_mfma_f32_16x16x32_bf16 v[28:31], v[128:131], v[192:195], v[28:31]
	v_mfma_f32_16x16x32_bf16 v[24:27], v[150:153], v[192:195], v[24:27]
	v_mfma_f32_16x16x32_bf16 v[12:15], v[128:131], v[200:203], v[12:15]
	v_mfma_f32_16x16x32_bf16 v[8:11], v[150:153], v[200:203], v[8:11]
	v_mfma_f32_16x16x32_bf16 v[60:63], v[132:135], v[180:183], v[60:63]
	v_mfma_f32_16x16x32_bf16 v[56:59], v[154:157], v[180:183], v[56:59]
	v_mfma_f32_16x16x32_bf16 v[44:47], v[132:135], v[188:191], v[44:47]
	v_mfma_f32_16x16x32_bf16 v[40:43], v[154:157], v[188:191], v[40:43]
	v_mfma_f32_16x16x32_bf16 v[28:31], v[132:135], v[196:199], v[28:31]
	v_mfma_f32_16x16x32_bf16 v[24:27], v[154:157], v[196:199], v[24:27]
	v_mfma_f32_16x16x32_bf16 v[12:15], v[132:135], v[206:209], v[12:15]
	v_mfma_f32_16x16x32_bf16 v[8:11], v[154:157], v[206:209], v[8:11]
	s_setprio 0
	s_setprio 1
	v_mfma_f32_16x16x32_bf16 v[52:55], v[158:161], v[174:177], v[52:55]
	v_mfma_f32_16x16x32_bf16 v[48:51], v[166:169], v[174:177], v[48:51]
	v_mfma_f32_16x16x32_bf16 v[36:39], v[158:161], v[184:187], v[36:39]
	v_mfma_f32_16x16x32_bf16 v[32:35], v[166:169], v[184:187], v[32:35]
	v_mfma_f32_16x16x32_bf16 v[20:23], v[158:161], v[192:195], v[20:23]
	v_mfma_f32_16x16x32_bf16 v[16:19], v[166:169], v[192:195], v[16:19]
	v_mfma_f32_16x16x32_bf16 v[4:7], v[158:161], v[200:203], v[4:7]
	v_mfma_f32_16x16x32_bf16 v[0:3], v[166:169], v[200:203], v[0:3]
	v_mfma_f32_16x16x32_bf16 v[52:55], v[162:165], v[180:183], v[52:55]
	v_mfma_f32_16x16x32_bf16 v[48:51], v[170:173], v[180:183], v[48:51]
	v_mfma_f32_16x16x32_bf16 v[36:39], v[162:165], v[188:191], v[36:39]
	v_mfma_f32_16x16x32_bf16 v[32:35], v[170:173], v[188:191], v[32:35]
	v_mfma_f32_16x16x32_bf16 v[20:23], v[162:165], v[196:199], v[20:23]
	v_mfma_f32_16x16x32_bf16 v[16:19], v[170:173], v[196:199], v[16:19]
	v_mfma_f32_16x16x32_bf16 v[4:7], v[162:165], v[206:209], v[4:7]
	v_mfma_f32_16x16x32_bf16 v[0:3], v[170:173], v[206:209], v[0:3]
	s_setprio 0
	s_barrier
	s_add_i32 s76, s76, 2
	s_add_u32 s42, s42, 0x100
	s_addc_u32 s43, s43, 0
	s_add_u32 s69, s69, 0x100
	s_addc_u32 s92, s92, 0
	s_cmp_gt_u32 s76, 29
	s_cbranch_scc0 .LBB0_319
	s_and_b64 vcc, exec, s[24:25]
	s_cbranch_vccz .LBB0_322
	s_barrier

; #define PG8_STAGE(bufoff, gbase, voff) do { _Pragma("unroll") for (int _i = 0; _i < 2; ++_i) \
;         __builtin_amdgcn_global_load_lds((const unsigned*)((const char*)(gbase) + (voff)[_i]), (PG8_LAS unsigned*)(lds + (bufoff) + ldsw + _i * 8192), 16, 0, 0); } while (0)
; #define PG8_LDA(dst, b, h) do { _Pragma("unroll") for (int m = 0; m < 4; ++m) _Pragma("unroll") for (int k = 0; k < 2; ++k) dst[m][k] = *(const PG8_LAS bf16x8*)(lds + PG8_SA(b, h) + aoff + m * 2048 + k * 1024); } while (0)
; #define PG8_LDB(dst, b, h) do { _Pragma("unroll") for (int n = 0; n < 2; ++n) _Pragma("unroll") for (int k = 0; k < 2; ++k) dst[n][k] = *(const PG8_LAS bf16x8*)(lds + PG8_SB(b, h) + boff + n * 2048 + k * 1024); } while (0)
; #define PG8_SCHED __builtin_amdgcn_sched_barrier(0)
; template <class Epi, class Sched, bool ALIGN_EPI = false, bool SP2 = false>
; __device__ __forceinline__ void gemm_phase(PG8_LAS unsigned char* lds, const Gemm g, const Sched& S, const Epi& E, const int tid) {
;     ...
;         const bool has_next = S.next(ui + 1, nxt);
;         const char* nA = has_next ? (const char*)g.A + (size_t)nxt.pm * tstep : cA; const char* nB = has_next ? (const char*)g.Bt + (size_t)nxt.pn * tstep : cB;
;         for (int t = 0; t < nt; t += 2) {
;             const bool last = (t == nt - 2);
;             const char* a1 = cA + (size_t)(t + 1) * kstep;
;             const char* a2 = last ? nA : cA + (size_t)(t + 2) * kstep; const char* b2 = last ? nB : cB + (size_t)(t + 2) * kstep;
;             const char* a3 = a2 + kstep; const char* b3 = b2 + kstep;
;             if (last && has_next) S.a_ready(nxt);
;             if constexpr (SP2) {
;             PG8_LDB(B0, 0, 0); PG8_LDB(B1, 0, 1); PG8_SCHED; PG8_LDA(At, 0, 0); PG8_STAGE(PG8_SA(1, 1), a1 + hstep, voffA);
;     ...
;         if constexpr (!Epi::ACC_INIT) {
; #pragma unroll
;         for (int a = 0; a < 2; ++a)
; #pragma unroll
;             for (int b = 0; b < 2; ++b)
; #pragma unroll
;                 for (int m = 0; m < 4; ++m)
; #pragma unroll
;                     for (int n = 0; n < 2; ++n) acc[a][b][m][n] = (f32x4){0.f, 0.f, 0.f, 0.f};
;         }
;         cur = nxt; cA = nA; cB = nB; ++ui;
.LBB0_679:
	s_ashr_i32 s29, s28, 31
	s_lshl_b64 s[30:31], s[28:29], 20
	s_add_u32 s30, s50, s30
	s_addc_u32 s31, s51, s31
	s_and_b64 s[34:35], s[6:7], exec
	s_cselect_b32 s29, s31, s45
	s_cselect_b32 s43, s30, s44
	s_ashr_i32 s27, s26, 31
	s_lshl_b64 s[34:35], s[26:27], 20
	s_add_u32 s34, s52, s34
	s_addc_u32 s35, s53, s35
	s_and_b64 s[48:49], s[6:7], exec
	s_cselect_b32 s27, s35, s47
	s_cselect_b32 s69, s34, s46
	s_add_u32 s44, s44, 0x80080
	s_addc_u32 s45, s45, 0
	s_add_u32 vcc_lo, s46, 0x100
	v_mov_b32_e32 v0, 0
	s_addc_u32 vcc_hi, s47, 0
	s_mov_b32 s76, -2
	v_mov_b32_e32 v1, v0
	v_mov_b32_e32 v2, v0
	v_mov_b32_e32 v3, v0
	v_mov_b32_e32 v4, v0
	v_mov_b32_e32 v5, v0
	v_mov_b32_e32 v6, v0
	v_mov_b32_e32 v7, v0
	v_mov_b32_e32 v16, v0
	v_mov_b32_e32 v17, v0
	v_mov_b32_e32 v18, v0
	v_mov_b32_e32 v19, v0
	v_mov_b32_e32 v20, v0
	v_mov_b32_e32 v21, v0
	v_mov_b32_e32 v22, v0
	v_mov_b32_e32 v23, v0
	v_mov_b32_e32 v32, v0
	v_mov_b32_e32 v33, v0
	v_mov_b32_e32 v34, v0
	v_mov_b32_e32 v35, v0
	v_mov_b32_e32 v36, v0
	v_mov_b32_e32 v37, v0
	v_mov_b32_e32 v38, v0
	v_mov_b32_e32 v39, v0
	v_mov_b32_e32 v48, v0
	v_mov_b32_e32 v49, v0
	v_mov_b32_e32 v50, v0
	v_mov_b32_e32 v51, v0
	v_mov_b32_e32 v52, v0
	v_mov_b32_e32 v53, v0
	v_mov_b32_e32 v54, v0
	v_mov_b32_e32 v55, v0
	v_mov_b32_e32 v8, v0
	v_mov_b32_e32 v9, v0
	v_mov_b32_e32 v10, v0
	v_mov_b32_e32 v11, v0
	v_mov_b32_e32 v12, v0
	v_mov_b32_e32 v13, v0
	v_mov_b32_e32 v14, v0
	v_mov_b32_e32 v15, v0
	v_mov_b32_e32 v24, v0
	v_mov_b32_e32 v25, v0
	v_mov_b32_e32 v26, v0
	v_mov_b32_e32 v27, v0
	v_mov_b32_e32 v28, v0
	v_mov_b32_e32 v29, v0
	v_mov_b32_e32 v30, v0
	v_mov_b32_e32 v31, v0
	v_mov_b32_e32 v40, v0
	v_mov_b32_e32 v41, v0
	v_mov_b32_e32 v42, v0
	v_mov_b32_e32 v43, v0
	v_mov_b32_e32 v44, v0
	v_mov_b32_e32 v45, v0
	v_mov_b32_e32 v46, v0
	v_mov_b32_e32 v47, v0
	v_mov_b32_e32 v56, v0
	v_mov_b32_e32 v57, v0
	v_mov_b32_e32 v58, v0
	v_mov_b32_e32 v59, v0
	v_mov_b32_e32 v60, v0
	v_mov_b32_e32 v61, v0
	v_mov_b32_e32 v62, v0
	v_mov_b32_e32 v63, v0
	v_mov_b32_e32 v64, v0
	v_mov_b32_e32 v65, v0
	v_mov_b32_e32 v66, v0
	v_mov_b32_e32 v67, v0
	v_mov_b32_e32 v68, v0
	v_mov_b32_e32 v69, v0
	v_mov_b32_e32 v70, v0
	v_mov_b32_e32 v71, v0
	v_mov_b32_e32 v80, v0
	v_mov_b32_e32 v81, v0
	v_mov_b32_e32 v82, v0
	v_mov_b32_e32 v83, v0
	v_mov_b32_e32 v84, v0
	v_mov_b32_e32 v85, v0
	v_mov_b32_e32 v86, v0
	v_mov_b32_e32 v87, v0
	v_mov_b32_e32 v96, v0
	v_mov_b32_e32 v97, v0
	v_mov_b32_e32 v98, v0
	v_mov_b32_e32 v99, v0
	v_mov_b32_e32 v100, v0
	v_mov_b32_e32 v101, v0
	v_mov_b32_e32 v102, v0
	v_mov_b32_e32 v103, v0
	v_mov_b32_e32 v112, v0
	v_mov_b32_e32 v113, v0
	v_mov_b32_e32 v114, v0
	v_mov_b32_e32 v115, v0
	v_mov_b32_e32 v116, v0
	v_mov_b32_e32 v117, v0
	v_mov_b32_e32 v118, v0
	v_mov_b32_e32 v119, v0
	v_mov_b32_e32 v72, v0
	v_mov_b32_e32 v73, v0
	v_mov_b32_e32 v74, v0
	v_mov_b32_e32 v75, v0
	v_mov_b32_e32 v76, v0
	v_mov_b32_e32 v77, v0
	v_mov_b32_e32 v78, v0
	v_mov_b32_e32 v79, v0
	v_mov_b32_e32 v88, v0
	v_mov_b32_e32 v89, v0
	v_mov_b32_e32 v90, v0
	v_mov_b32_e32 v91, v0
	v_mov_b32_e32 v92, v0
	v_mov_b32_e32 v93, v0
	v_mov_b32_e32 v94, v0
	v_mov_b32_e32 v95, v0
	v_mov_b32_e32 v104, v0
	v_mov_b32_e32 v105, v0
	v_mov_b32_e32 v106, v0
	v_mov_b32_e32 v107, v0
	v_mov_b32_e32 v108, v0
	v_mov_b32_e32 v109, v0
	v_mov_b32_e32 v110, v0
	v_mov_b32_e32 v111, v0
	v_mov_b32_e32 v120, v0
	v_mov_b32_e32 v121, v0
	v_mov_b32_e32 v122, v0
	v_mov_b32_e32 v123, v0
	v_mov_b32_e32 v124, v0
	v_mov_b32_e32 v125, v0
	v_mov_b32_e32 v126, v0
	v_mov_b32_e32 v127, v0
	s_waitcnt vmcnt(0)
.LBB0_680:
	s_add_u32 s46, s44, 0xfff80080
	s_addc_u32 s47, s45, -1
	s_add_i32 s77, 0, 0x10000
	s_cmp_eq_u32 s76, 28
	s_cselect_b32 s49, s29, s47
	s_cselect_b32 s48, s43, s46
	s_cselect_b32 s47, s27, vcc_hi
	s_cselect_b32 s46, s69, vcc_lo
	s_add_i32 s80, 0, 0x14000
	v_add_u32_e32 v152, s77, v166
	v_add_u32_e32 v164, s80, v166
	ds_read_b128 v[128:131], v152
	ds_read_b128 v[144:147], v152 offset:1024
	ds_read_b128 v[148:151], v152 offset:2048
	ds_read_b128 v[152:155], v152 offset:3072
	ds_read_b128 v[156:159], v164
	ds_read_b128 v[160:163], v164 offset:1024
	ds_read_b128 v[168:171], v164 offset:2048
	ds_read_b128 v[172:175], v164 offset:3072
	v_lshl_add_u64 v[164:165], s[44:45], 0, v[140:141]
	s_add_i32 m0, s37, 0xc000
	ds_read_b128 v[176:179], v167
	ds_read_b128 v[180:183], v167 offset:1024
	ds_read_b128 v[184:187], v167 offset:2048
	ds_read_b128 v[188:191], v167 offset:3072
	ds_read_b128 v[192:195], v167 offset:4096
	ds_read_b128 v[196:199], v167 offset:5120
	ds_read_b128 v[200:203], v167 offset:6144
	ds_read_b128 v[214:217], v167 offset:7168
	global_load_lds_dwordx4 v[164:165], off
	v_lshl_add_u64 v[164:165], s[44:45], 0, v[142:143]
	s_add_i32 m0, s37, 0xe000
	s_nop 0
	global_load_lds_dwordx4 v[164:165], off
	s_waitcnt vmcnt(8)
	s_waitcnt lgkmcnt(0)
	s_barrier
; #define PG8_STAGE(bufoff, gbase, voff) do { _Pragma("unroll") for (int _i = 0; _i < 2; ++_i) \
;         __builtin_amdgcn_global_load_lds((const unsigned*)((const char*)(gbase) + (voff)[_i]), (PG8_LAS unsigned*)(lds + (bufoff) + ldsw + _i * 8192), 16, 0, 0); } while (0)
; #define PG8_LDA(dst, b, h) do { _Pragma("unroll") for (int m = 0; m < 4; ++m) _Pragma("unroll") for (int k = 0; k < 2; ++k) dst[m][k] = *(const PG8_LAS bf16x8*)(lds + PG8_SA(b, h) + aoff + m * 2048 + k * 1024); } while (0)
; #define PG8_LDB(dst, b, h) do { _Pragma("unroll") for (int n = 0; n < 2; ++n) _Pragma("unroll") for (int k = 0; k < 2; ++k) dst[n][k] = *(const PG8_LAS bf16x8*)(lds + PG8_SB(b, h) + boff + n * 2048 + k * 1024); } while (0)
; #define PG8_MMA(ai, bj, At, Bt) do { __builtin_amdgcn_s_setprio(1); _Pragma("unroll") for (int m = 0; m < 4; ++m) _Pragma("unroll") for (int n = 0; n < 2; ++n) _Pragma("unroll") for (int k = 0; k < 2; ++k) \
;         acc[ai][bj][m][n] = __builtin_amdgcn_mfma_f32_16x16x32_bf16(Bt[n][k], At[m][k], acc[ai][bj][m][n], 0, 0, 0); __builtin_amdgcn_s_setprio(0); } while (0)
; #define PG8_WAIT_V(n) asm volatile("s_waitcnt vmcnt(" #n ")" ::: "memory")
; #define PG8_WAIT_L(n) asm volatile("s_waitcnt lgkmcnt(" #n ")" ::: "memory")
; #define PG8_BAR __builtin_amdgcn_s_barrier()
; #define PG8_SCHED __builtin_amdgcn_sched_barrier(0)
; template <class Epi, class Sched, bool ALIGN_EPI = false, bool SP2 = false>
; __device__ __forceinline__ void gemm_phase(PG8_LAS unsigned char* lds, const Gemm g, const Sched& S, const Epi& E, const int tid) {
;     ...
;             PG8_LDB(B0, 0, 0); PG8_LDB(B1, 0, 1); PG8_SCHED; PG8_LDA(At, 0, 0); PG8_STAGE(PG8_SA(1, 1), a1 + hstep, voffA);
;             PG8_WAIT_V(8); PG8_WAIT_L(0); PG8_BAR; PG8_MMA(0, 0, At, B0); PG8_MMA(0, 1, At, B1); PG8_BAR; PG8_SCHED;
;             PG8_LDA(At, 0, 1); PG8_STAGE(PG8_SB(0, 0), b2, voffB); PG8_STAGE(PG8_SB(0, 1), b2 + hstep, voffB); PG8_STAGE(PG8_SA(0, 0), a2, voffA);
;             PG8_WAIT_V(8); PG8_WAIT_L(0); PG8_BAR; PG8_MMA(1, 0, At, B0); PG8_MMA(1, 1, At, B1); PG8_BAR; PG8_SCHED;
	s_setprio 1
	s_waitcnt lgkmcnt(0)
	v_mfma_f32_16x16x32_bf16 v[124:127], v[128:131], v[176:179], v[124:127]
	v_mfma_f32_16x16x32_bf16 v[120:123], v[148:151], v[176:179], v[120:123]
	v_mfma_f32_16x16x32_bf16 v[108:111], v[128:131], v[184:187], v[108:111]
	v_mfma_f32_16x16x32_bf16 v[104:107], v[148:151], v[184:187], v[104:107]
	v_mfma_f32_16x16x32_bf16 v[92:95], v[128:131], v[192:195], v[92:95]
	v_mfma_f32_16x16x32_bf16 v[88:91], v[148:151], v[192:195], v[88:91]
	v_mfma_f32_16x16x32_bf16 v[76:79], v[128:131], v[200:203], v[76:79]
	v_mfma_f32_16x16x32_bf16 v[72:75], v[148:151], v[200:203], v[72:75]
	v_mfma_f32_16x16x32_bf16 v[124:127], v[144:147], v[180:183], v[124:127]
	v_mfma_f32_16x16x32_bf16 v[120:123], v[152:155], v[180:183], v[120:123]
	v_mfma_f32_16x16x32_bf16 v[108:111], v[144:147], v[188:191], v[108:111]
	v_mfma_f32_16x16x32_bf16 v[104:107], v[152:155], v[188:191], v[104:107]
	v_mfma_f32_16x16x32_bf16 v[92:95], v[144:147], v[196:199], v[92:95]
	v_mfma_f32_16x16x32_bf16 v[88:91], v[152:155], v[196:199], v[88:91]
	v_mfma_f32_16x16x32_bf16 v[76:79], v[144:147], v[214:217], v[76:79]
	v_mfma_f32_16x16x32_bf16 v[72:75], v[152:155], v[214:217], v[72:75]
	s_setprio 0
	s_setprio 1
	v_mfma_f32_16x16x32_bf16 v[116:119], v[156:159], v[176:179], v[116:119]
	v_mfma_f32_16x16x32_bf16 v[112:115], v[168:171], v[176:179], v[112:115]
	v_mfma_f32_16x16x32_bf16 v[100:103], v[156:159], v[184:187], v[100:103]
	v_mfma_f32_16x16x32_bf16 v[96:99], v[168:171], v[184:187], v[96:99]
	v_mfma_f32_16x16x32_bf16 v[84:87], v[156:159], v[192:195], v[84:87]
	v_mfma_f32_16x16x32_bf16 v[80:83], v[168:171], v[192:195], v[80:83]
	v_mfma_f32_16x16x32_bf16 v[68:71], v[156:159], v[200:203], v[68:71]
	v_mfma_f32_16x16x32_bf16 v[64:67], v[168:171], v[200:203], v[64:67]
	v_mfma_f32_16x16x32_bf16 v[116:119], v[160:163], v[180:183], v[116:119]
	v_mfma_f32_16x16x32_bf16 v[112:115], v[172:175], v[180:183], v[112:115]
	v_mfma_f32_16x16x32_bf16 v[100:103], v[160:163], v[188:191], v[100:103]
	v_mfma_f32_16x16x32_bf16 v[96:99], v[172:175], v[188:191], v[96:99]
	v_mfma_f32_16x16x32_bf16 v[84:87], v[160:163], v[196:199], v[84:87]
	v_mfma_f32_16x16x32_bf16 v[80:83], v[172:175], v[196:199], v[80:83]
	v_mfma_f32_16x16x32_bf16 v[68:71], v[160:163], v[214:217], v[68:71]
	v_mfma_f32_16x16x32_bf16 v[64:67], v[172:175], v[214:217], v[64:67]
	s_setprio 0
	s_barrier
	s_add_i32 s77, s77, s54
	v_lshl_add_u64 v[164:165], s[46:47], 0, v[134:135]
	s_mov_b32 m0, s77
	ds_read_b128 v[176:179], v167 offset:16384
	ds_read_b128 v[180:183], v167 offset:17408
	ds_read_b128 v[184:187], v167 offset:18432
	ds_read_b128 v[188:191], v167 offset:19456
	ds_read_b128 v[192:195], v167 offset:20480
	ds_read_b128 v[196:199], v167 offset:21504
	ds_read_b128 v[200:203], v167 offset:22528
	ds_read_b128 v[214:217], v167 offset:23552
	global_load_lds_dwordx4 v[164:165], off
	s_add_i32 m0, s77, 0x2000
	s_add_u32 s78, s46, 0x80000
	v_lshl_add_u64 v[206:207], s[46:47], 0, v[138:139]
	s_addc_u32 s79, s47, 0
	s_add_i32 s77, s80, s54
	global_load_lds_dwordx4 v[206:207], off
	v_lshl_add_u64 v[208:209], s[78:79], 0, v[134:135]
	s_mov_b32 m0, s77
	v_lshl_add_u64 v[210:211], s[48:49], 0, v[136:137]
	global_load_lds_dwordx4 v[208:209], off
	v_lshl_add_u64 v[208:209], s[78:79], 0, v[138:139]
	s_add_i32 m0, s77, 0x2000
	s_nop 0
	global_load_lds_dwordx4 v[208:209], off
	v_lshl_add_u64 v[208:209], s[48:49], 0, v[132:133]
	s_mov_b32 m0, s37
	s_nop 0
	global_load_lds_dwordx4 v[208:209], off
	s_mov_b32 m0, s55
	s_nop 0
	global_load_lds_dwordx4 v[210:211], off
	s_waitcnt vmcnt(8)
	s_waitcnt lgkmcnt(0)
	s_barrier
	s_setprio 1
	s_waitcnt lgkmcnt(0)
	v_mfma_f32_16x16x32_bf16 v[60:63], v[128:131], v[176:179], v[60:63]
	v_mfma_f32_16x16x32_bf16 v[56:59], v[148:151], v[176:179], v[56:59]
	v_mfma_f32_16x16x32_bf16 v[44:47], v[128:131], v[184:187], v[44:47]
	v_mfma_f32_16x16x32_bf16 v[40:43], v[148:151], v[184:187], v[40:43]
	v_mfma_f32_16x16x32_bf16 v[28:31], v[128:131], v[192:195], v[28:31]
	v_mfma_f32_16x16x32_bf16 v[24:27], v[148:151], v[192:195], v[24:27]
	v_mfma_f32_16x16x32_bf16 v[12:15], v[128:131], v[200:203], v[12:15]
	v_mfma_f32_16x16x32_bf16 v[8:11], v[148:151], v[200:203], v[8:11]
	v_mfma_f32_16x16x32_bf16 v[60:63], v[144:147], v[180:183], v[60:63]
	v_mfma_f32_16x16x32_bf16 v[56:59], v[152:155], v[180:183], v[56:59]
	v_mfma_f32_16x16x32_bf16 v[44:47], v[144:147], v[188:191], v[44:47]
	v_mfma_f32_16x16x32_bf16 v[40:43], v[152:155], v[188:191], v[40:43]
	v_mfma_f32_16x16x32_bf16 v[28:31], v[144:147], v[196:199], v[28:31]
	v_mfma_f32_16x16x32_bf16 v[24:27], v[152:155], v[196:199], v[24:27]
	v_mfma_f32_16x16x32_bf16 v[12:15], v[144:147], v[214:217], v[12:15]
	v_mfma_f32_16x16x32_bf16 v[8:11], v[152:155], v[214:217], v[8:11]
	s_setprio 0
	s_setprio 1
	v_mfma_f32_16x16x32_bf16 v[52:55], v[156:159], v[176:179], v[52:55]
	v_mfma_f32_16x16x32_bf16 v[48:51], v[168:171], v[176:179], v[48:51]
	v_mfma_f32_16x16x32_bf16 v[36:39], v[156:159], v[184:187], v[36:39]
	v_mfma_f32_16x16x32_bf16 v[32:35], v[168:171], v[184:187], v[32:35]
	v_mfma_f32_16x16x32_bf16 v[20:23], v[156:159], v[192:195], v[20:23]
	v_mfma_f32_16x16x32_bf16 v[16:19], v[168:171], v[192:195], v[16:19]
	v_mfma_f32_16x16x32_bf16 v[4:7], v[156:159], v[200:203], v[4:7]
	v_mfma_f32_16x16x32_bf16 v[0:3], v[168:171], v[200:203], v[0:3]
	v_mfma_f32_16x16x32_bf16 v[52:55], v[160:163], v[180:183], v[52:55]
	v_mfma_f32_16x16x32_bf16 v[48:51], v[172:175], v[180:183], v[48:51]
	v_mfma_f32_16x16x32_bf16 v[36:39], v[160:163], v[188:191], v[36:39]
	v_mfma_f32_16x16x32_bf16 v[32:35], v[172:175], v[188:191], v[32:35]
	v_mfma_f32_16x16x32_bf16 v[20:23], v[160:163], v[196:199], v[20:23]
	v_mfma_f32_16x16x32_bf16 v[16:19], v[172:175], v[196:199], v[16:19]
	v_mfma_f32_16x16x32_bf16 v[4:7], v[160:163], v[214:217], v[4:7]
	v_mfma_f32_16x16x32_bf16 v[0:3], v[172:175], v[214:217], v[0:3]
	s_setprio 0
	s_barrier
; #define PG8_STAGE(bufoff, gbase, voff) do { _Pragma("unroll") for (int _i = 0; _i < 2; ++_i) \
;         __builtin_amdgcn_global_load_lds((const unsigned*)((const char*)(gbase) + (voff)[_i]), (PG8_LAS unsigned*)(lds + (bufoff) + ldsw + _i * 8192), 16, 0, 0); } while (0)
; #define PG8_LDA(dst, b, h) do { _Pragma("unroll") for (int m = 0; m < 4; ++m) _Pragma("unroll") for (int k = 0; k < 2; ++k) dst[m][k] = *(const PG8_LAS bf16x8*)(lds + PG8_SA(b, h) + aoff + m * 2048 + k * 1024); } while (0)
; #define PG8_LDB(dst, b, h) do { _Pragma("unroll") for (int n = 0; n < 2; ++n) _Pragma("unroll") for (int k = 0; k < 2; ++k) dst[n][k] = *(const PG8_LAS bf16x8*)(lds + PG8_SB(b, h) + boff + n * 2048 + k * 1024); } while (0)
; #define PG8_MMA(ai, bj, At, Bt) do { __builtin_amdgcn_s_setprio(1); _Pragma("unroll") for (int m = 0; m < 4; ++m) _Pragma("unroll") for (int n = 0; n < 2; ++n) _Pragma("unroll") for (int k = 0; k < 2; ++k) \
;         acc[ai][bj][m][n] = __builtin_amdgcn_mfma_f32_16x16x32_bf16(Bt[n][k], At[m][k], acc[ai][bj][m][n], 0, 0, 0); __builtin_amdgcn_s_setprio(0); } while (0)
; #define PG8_WAIT_V(n) asm volatile("s_waitcnt vmcnt(" #n ")" ::: "memory")
; #define PG8_WAIT_L(n) asm volatile("s_waitcnt lgkmcnt(" #n ")" ::: "memory")
; #define PG8_BAR __builtin_amdgcn_s_barrier()
; #define PG8_SCHED __builtin_amdgcn_sched_barrier(0)
; template <class Epi, class Sched, bool ALIGN_EPI = false, bool SP2 = false>
; __device__ __forceinline__ void gemm_phase(PG8_LAS unsigned char* lds, const Gemm g, const Sched& S, const Epi& E, const int tid) {
;     ...
;             PG8_LDB(B0, 1, 0); PG8_LDB(B1, 1, 1); PG8_SCHED; PG8_LDA(At, 1, 0); PG8_STAGE(PG8_SA(0, 1), a2 + hstep, voffA);
;             PG8_WAIT_V(8); PG8_WAIT_L(0); PG8_BAR; PG8_MMA(0, 0, At, B0); PG8_MMA(0, 1, At, B1); PG8_BAR; PG8_SCHED;
	s_add_i32 s77, 0, 0x18000
	s_add_i32 s78, 0, 0x1c000
	v_add_u32_e32 v152, s77, v166
	v_add_u32_e32 v172, s78, v166
	ds_read_b128 v[128:131], v152
	ds_read_b128 v[144:147], v152 offset:1024
	ds_read_b128 v[148:151], v152 offset:2048
	ds_read_b128 v[152:155], v152 offset:3072
	ds_read_b128 v[156:159], v172
	ds_read_b128 v[160:163], v172 offset:1024
	ds_read_b128 v[168:171], v172 offset:2048
	ds_read_b128 v[172:175], v172 offset:3072
	s_add_u32 s48, s48, 0x80000
	s_addc_u32 s49, s49, 0
	s_mov_b32 m0, s0
	v_lshl_add_u64 v[212:213], s[48:49], 0, v[132:133]
	ds_read_b128 v[176:179], v167 offset:32768
	ds_read_b128 v[180:183], v167 offset:33792
	ds_read_b128 v[184:187], v167 offset:34816
	ds_read_b128 v[188:191], v167 offset:35840
	ds_read_b128 v[192:195], v167 offset:36864
	ds_read_b128 v[196:199], v167 offset:37888
	ds_read_b128 v[200:203], v167 offset:38912
	ds_read_b128 v[214:217], v167 offset:39936
	global_load_lds_dwordx4 v[212:213], off
	v_lshl_add_u64 v[212:213], s[48:49], 0, v[136:137]
	s_mov_b32 m0, s33
	s_nop 0
	global_load_lds_dwordx4 v[212:213], off
	s_waitcnt vmcnt(8)
	s_waitcnt lgkmcnt(0)
	s_barrier
	s_setprio 1
	s_waitcnt lgkmcnt(0)
	v_mfma_f32_16x16x32_bf16 v[124:127], v[128:131], v[176:179], v[124:127]
	v_mfma_f32_16x16x32_bf16 v[120:123], v[148:151], v[176:179], v[120:123]
	v_mfma_f32_16x16x32_bf16 v[108:111], v[128:131], v[184:187], v[108:111]
	v_mfma_f32_16x16x32_bf16 v[104:107], v[148:151], v[184:187], v[104:107]
	v_mfma_f32_16x16x32_bf16 v[92:95], v[128:131], v[192:195], v[92:95]
	v_mfma_f32_16x16x32_bf16 v[88:91], v[148:151], v[192:195], v[88:91]
	v_mfma_f32_16x16x32_bf16 v[76:79], v[128:131], v[200:203], v[76:79]
	v_mfma_f32_16x16x32_bf16 v[72:75], v[148:151], v[200:203], v[72:75]
	v_mfma_f32_16x16x32_bf16 v[124:127], v[144:147], v[180:183], v[124:127]
	v_mfma_f32_16x16x32_bf16 v[120:123], v[152:155], v[180:183], v[120:123]
	v_mfma_f32_16x16x32_bf16 v[108:111], v[144:147], v[188:191], v[108:111]
	v_mfma_f32_16x16x32_bf16 v[104:107], v[152:155], v[188:191], v[104:107]
	v_mfma_f32_16x16x32_bf16 v[92:95], v[144:147], v[196:199], v[92:95]
	v_mfma_f32_16x16x32_bf16 v[88:91], v[152:155], v[196:199], v[88:91]
	v_mfma_f32_16x16x32_bf16 v[76:79], v[144:147], v[214:217], v[76:79]
	v_mfma_f32_16x16x32_bf16 v[72:75], v[152:155], v[214:217], v[72:75]
	s_setprio 0
	s_setprio 1
	v_mfma_f32_16x16x32_bf16 v[116:119], v[156:159], v[176:179], v[116:119]
	v_mfma_f32_16x16x32_bf16 v[112:115], v[168:171], v[176:179], v[112:115]
	v_mfma_f32_16x16x32_bf16 v[100:103], v[156:159], v[184:187], v[100:103]
	v_mfma_f32_16x16x32_bf16 v[96:99], v[168:171], v[184:187], v[96:99]
	v_mfma_f32_16x16x32_bf16 v[84:87], v[156:159], v[192:195], v[84:87]
	v_mfma_f32_16x16x32_bf16 v[80:83], v[168:171], v[192:195], v[80:83]
	v_mfma_f32_16x16x32_bf16 v[68:71], v[156:159], v[200:203], v[68:71]
	v_mfma_f32_16x16x32_bf16 v[64:67], v[168:171], v[200:203], v[64:67]
	v_mfma_f32_16x16x32_bf16 v[116:119], v[160:163], v[180:183], v[116:119]
	v_mfma_f32_16x16x32_bf16 v[112:115], v[172:175], v[180:183], v[112:115]
	v_mfma_f32_16x16x32_bf16 v[100:103], v[160:163], v[188:191], v[100:103]
	v_mfma_f32_16x16x32_bf16 v[96:99], v[172:175], v[188:191], v[96:99]
	v_mfma_f32_16x16x32_bf16 v[84:87], v[160:163], v[196:199], v[84:87]
	v_mfma_f32_16x16x32_bf16 v[80:83], v[172:175], v[196:199], v[80:83]
	v_mfma_f32_16x16x32_bf16 v[68:71], v[160:163], v[214:217], v[68:71]
	v_mfma_f32_16x16x32_bf16 v[64:67], v[172:175], v[214:217], v[64:67]
	s_setprio 0
	s_barrier
; #define PG8_STAGE(bufoff, gbase, voff) do { _Pragma("unroll") for (int _i = 0; _i < 2; ++_i) \
;         __builtin_amdgcn_global_load_lds((const unsigned*)((const char*)(gbase) + (voff)[_i]), (PG8_LAS unsigned*)(lds + (bufoff) + ldsw + _i * 8192), 16, 0, 0); } while (0)
; #define PG8_LDA(dst, b, h) do { _Pragma("unroll") for (int m = 0; m < 4; ++m) _Pragma("unroll") for (int k = 0; k < 2; ++k) dst[m][k] = *(const PG8_LAS bf16x8*)(lds + PG8_SA(b, h) + aoff + m * 2048 + k * 1024); } while (0)
; #define PG8_MMA(ai, bj, At, Bt) do { __builtin_amdgcn_s_setprio(1); _Pragma("unroll") for (int m = 0; m < 4; ++m) _Pragma("unroll") for (int n = 0; n < 2; ++n) _Pragma("unroll") for (int k = 0; k < 2; ++k) \
;         acc[ai][bj][m][n] = __builtin_amdgcn_mfma_f32_16x16x32_bf16(Bt[n][k], At[m][k], acc[ai][bj][m][n], 0, 0, 0); __builtin_amdgcn_s_setprio(0); } while (0)
; #define PG8_WAIT_V(n) asm volatile("s_waitcnt vmcnt(" #n ")" ::: "memory")
; #define PG8_WAIT_L(n) asm volatile("s_waitcnt lgkmcnt(" #n ")" ::: "memory")
; #define PG8_BAR __builtin_amdgcn_s_barrier()
; #define PG8_SCHED __builtin_amdgcn_sched_barrier(0)
; template <class Epi, class Sched, bool ALIGN_EPI = false, bool SP2 = false>
; __device__ __forceinline__ void gemm_phase(PG8_LAS unsigned char* lds, const Gemm g, const Sched& S, const Epi& E, const int tid) {
;     ...
;         for (int t = 0; t < nt; t += 2) {
;     ...
;             PG8_LDA(At, 1, 1); PG8_STAGE(PG8_SB(1, 0), b3, voffB); PG8_STAGE(PG8_SB(1, 1), b3 + hstep, voffB); PG8_STAGE(PG8_SA(1, 0), a3, voffA);
;             PG8_WAIT_V(8); PG8_WAIT_L(0); PG8_BAR; PG8_MMA(1, 0, At, B0); PG8_MMA(1, 1, At, B1); PG8_BAR; PG8_SCHED;
	s_add_i32 s48, s77, s54
	v_lshl_add_u64 v[164:165], v[164:165], 0, s[70:71]
	s_mov_b32 m0, s48
	ds_read_b128 v[176:179], v167 offset:49152
	ds_read_b128 v[180:183], v167 offset:50176
	ds_read_b128 v[184:187], v167 offset:51200
	ds_read_b128 v[188:191], v167 offset:52224
	ds_read_b128 v[192:195], v167 offset:53248
	ds_read_b128 v[196:199], v167 offset:54272
	ds_read_b128 v[200:203], v167 offset:55296
	ds_read_b128 v[214:217], v167 offset:56320
	global_load_lds_dwordx4 v[164:165], off
	s_add_i32 m0, s48, 0x2000
	s_add_u32 s46, s46, 0x80080
	v_lshl_add_u64 v[164:165], v[206:207], 0, s[70:71]
	s_addc_u32 s47, s47, 0
	s_add_i32 s48, s78, s54
	global_load_lds_dwordx4 v[164:165], off
	v_lshl_add_u64 v[164:165], s[46:47], 0, v[134:135]
	s_mov_b32 m0, s48
	s_nop 0
	global_load_lds_dwordx4 v[164:165], off
	v_lshl_add_u64 v[164:165], s[46:47], 0, v[138:139]
	s_add_i32 m0, s48, 0x2000
	s_nop 0
	global_load_lds_dwordx4 v[164:165], off
	v_lshl_add_u64 v[164:165], v[208:209], 0, s[70:71]
	s_mov_b32 m0, s10
	s_nop 0
	global_load_lds_dwordx4 v[164:165], off
	v_lshl_add_u64 v[164:165], v[210:211], 0, s[70:71]
	s_mov_b32 m0, s11
	s_nop 0
	global_load_lds_dwordx4 v[164:165], off
	s_waitcnt vmcnt(8)
	s_waitcnt lgkmcnt(0)
	s_barrier
	s_setprio 1
	s_waitcnt lgkmcnt(0)
	v_mfma_f32_16x16x32_bf16 v[60:63], v[128:131], v[176:179], v[60:63]
	v_mfma_f32_16x16x32_bf16 v[56:59], v[148:151], v[176:179], v[56:59]
	v_mfma_f32_16x16x32_bf16 v[44:47], v[128:131], v[184:187], v[44:47]
	v_mfma_f32_16x16x32_bf16 v[40:43], v[148:151], v[184:187], v[40:43]
	v_mfma_f32_16x16x32_bf16 v[28:31], v[128:131], v[192:195], v[28:31]
	v_mfma_f32_16x16x32_bf16 v[24:27], v[148:151], v[192:195], v[24:27]
	v_mfma_f32_16x16x32_bf16 v[12:15], v[128:131], v[200:203], v[12:15]
	v_mfma_f32_16x16x32_bf16 v[8:11], v[148:151], v[200:203], v[8:11]
	v_mfma_f32_16x16x32_bf16 v[60:63], v[144:147], v[180:183], v[60:63]
	v_mfma_f32_16x16x32_bf16 v[56:59], v[152:155], v[180:183], v[56:59]
	v_mfma_f32_16x16x32_bf16 v[44:47], v[144:147], v[188:191], v[44:47]
	v_mfma_f32_16x16x32_bf16 v[40:43], v[152:155], v[188:191], v[40:43]
	v_mfma_f32_16x16x32_bf16 v[28:31], v[144:147], v[196:199], v[28:31]
	v_mfma_f32_16x16x32_bf16 v[24:27], v[152:155], v[196:199], v[24:27]
	v_mfma_f32_16x16x32_bf16 v[12:15], v[144:147], v[214:217], v[12:15]
	v_mfma_f32_16x16x32_bf16 v[8:11], v[152:155], v[214:217], v[8:11]
	s_setprio 0
	s_setprio 1
	v_mfma_f32_16x16x32_bf16 v[52:55], v[156:159], v[176:179], v[52:55]
	v_mfma_f32_16x16x32_bf16 v[48:51], v[168:171], v[176:179], v[48:51]
	v_mfma_f32_16x16x32_bf16 v[36:39], v[156:159], v[184:187], v[36:39]
	v_mfma_f32_16x16x32_bf16 v[32:35], v[168:171], v[184:187], v[32:35]
	v_mfma_f32_16x16x32_bf16 v[20:23], v[156:159], v[192:195], v[20:23]
	v_mfma_f32_16x16x32_bf16 v[16:19], v[168:171], v[192:195], v[16:19]
	v_mfma_f32_16x16x32_bf16 v[4:7], v[156:159], v[200:203], v[4:7]
	v_mfma_f32_16x16x32_bf16 v[0:3], v[168:171], v[200:203], v[0:3]
	v_mfma_f32_16x16x32_bf16 v[52:55], v[160:163], v[180:183], v[52:55]
	v_mfma_f32_16x16x32_bf16 v[48:51], v[172:175], v[180:183], v[48:51]
	v_mfma_f32_16x16x32_bf16 v[36:39], v[160:163], v[188:191], v[36:39]
	v_mfma_f32_16x16x32_bf16 v[32:35], v[172:175], v[188:191], v[32:35]
	v_mfma_f32_16x16x32_bf16 v[20:23], v[160:163], v[196:199], v[20:23]
	v_mfma_f32_16x16x32_bf16 v[16:19], v[172:175], v[196:199], v[16:19]
	v_mfma_f32_16x16x32_bf16 v[4:7], v[160:163], v[214:217], v[4:7]
	v_mfma_f32_16x16x32_bf16 v[0:3], v[172:175], v[214:217], v[0:3]
	s_setprio 0
	s_barrier
	s_add_i32 s76, s76, 2
	s_add_u32 s44, s44, 0x100
	s_addc_u32 s45, s45, 0
	s_add_u32 vcc_lo, vcc_lo, 0x100
	s_addc_u32 vcc_hi, vcc_hi, 0
	s_cmp_gt_u32 s76, 29
	s_cbranch_scc0 .LBB0_680
	s_and_b64 vcc, exec, s[22:23]
	s_cbranch_vccz .LBB0_683
	s_barrier

; #define ATT_SBAR() __builtin_amdgcn_sched_barrier(0)
; #define ATT_QRD(dst, g) do { _Pragma("unroll") for (int t = 0; t < 2; ++t) { const int cb = ((2 * (g) + t) * 16 + hi * 8) * 2; \
;     dst[2 * t] = *reinterpret_cast<const bf16x8*>(kr + (cb ^ sw)); dst[2 * t + 1] = *reinterpret_cast<const bf16x8*>(kr + 32 * CF::KPITCH + (cb ^ sw)); } } while (0)
; #define ATT_QEARLY(dst, g) do { } while (0)
; #define ATT_QEARLY(dst, g) ATT_QRD(dst, g)
; template <class CF> __device__ __forceinline__ void qk_sm(f32x16& n0, f32x16& n1, const char* Ks, const bf16x8* qr, int r32, int hi,
;                                                           f32x16& p0, f32x16& p1, float alpha, float& l_reg, bf16x8& pa0, bf16x8& pa1, bf16x8& pa2, bf16x8& pa3) {
;   n0 = f32x16{}; n1 = f32x16{};
;   const char* kr = Ks + r32 * CF::KPITCH; const int sw = (r32 & CF::KSWM) << 4;
;   bf16x8 ka[4], kb[4];
;     ...
;   ATT_QRD(ka, 0); ATT_QRD(kb, 1); asm volatile("s_waitcnt lgkmcnt(4)" ::: "memory"); ATT_SBAR();
;     ...
;   ATT_QRD(ka, 0); asm volatile("s_waitcnt lgkmcnt(0)" ::: "memory"); ATT_SBAR();
;     ...
;   ATT_QEARLY(kb, 1);
; #pragma unroll
;   for (int r = 0; r < 16; ++r) p1[r] = __builtin_amdgcn_exp2f(p1[r]);
;   asm volatile("" : "+v"(p1));
;   ATT_QMM(ka, 0);
;     ...
;   ATT_QRD(ka, 2); asm volatile("s_waitcnt lgkmcnt(4)" ::: "memory"); ATT_SBAR();
;     ...
;   asm volatile("s_waitcnt lgkmcnt(0)" ::: "memory"); ATT_SBAR();
;     ...
;   ATT_QEARLY(ka, 2);
;   float ps = 0;
; #pragma unroll
;   for (int r = 0; r < 16; ++r) ps += p0[r];
; #pragma unroll
;   for (int r = 0; r < 16; ++r) ps += p1[r];
;   asm volatile("" : "+v"(ps));
;   ATT_QMM(kb, 1);
;     ...
;   ATT_QRD(kb, 3); asm volatile("s_waitcnt lgkmcnt(4)" ::: "memory"); ATT_SBAR();
;     ...
;   asm volatile("s_waitcnt lgkmcnt(0)" ::: "memory"); ATT_SBAR();
;     ...
;   ATT_QEARLY(kb, 3);
;   { auto rr = __builtin_amdgcn_permlane32_swap(__float_as_uint(ps), __float_as_uint(ps), false, false);
;     ps = __uint_as_float(rr[0]) + __uint_as_float(rr[1]); }
;   l_reg = l_reg * alpha + ps;
;   ATT_PK4(p0, 0, pa0); ATT_PK4(p0, 8, pa1);
;   asm volatile("" : "+v"(l_reg), "+v"(pa0), "+v"(pa1));
;   ATT_QMM(ka, 2);
;   asm volatile("s_waitcnt lgkmcnt(0)" ::: "memory"); ATT_SBAR();
;   ATT_PK4(p1, 0, pa2); ATT_PK4(p1, 8, pa3);
;   asm volatile("" : "+v"(pa2), "+v"(pa3));
;   ATT_QMM(kb, 3);
;     ...
;     ATT_SLOAD(SO, (j + SDEPTH) * KVBLK); ATT_SBAR();
.LBB0_803:
	ds_read_b128 v[206:209], v229 offset:49152
	ds_read_b128 v[210:213], v229 offset:57344
	ds_read_b128 v[218:221], v236 offset:49152
	ds_read_b128 v[250:253], v236 offset:57344
	s_waitcnt lgkmcnt(3)
	v_mfma_f32_32x32x16_bf16 v[112:127], v[206:209], v[156:159], 0
	v_exp_f32_e32 v80, v80
	v_exp_f32_e32 v81, v81
	v_exp_f32_e32 v82, v82
	v_exp_f32_e32 v83, v83
	v_exp_f32_e32 v84, v84
	v_exp_f32_e32 v85, v85
	v_exp_f32_e32 v86, v86
	s_waitcnt lgkmcnt(2)
	v_mfma_f32_32x32x16_bf16 v[96:111], v[210:213], v[156:159], 0
	v_exp_f32_e32 v87, v87
	v_exp_f32_e32 v88, v88
	v_exp_f32_e32 v89, v89
	v_exp_f32_e32 v90, v90
	v_exp_f32_e32 v91, v91
	v_exp_f32_e32 v92, v92
	v_exp_f32_e32 v93, v93
	s_waitcnt lgkmcnt(1)
	v_mfma_f32_32x32x16_bf16 v[112:127], v[218:221], v[152:155], v[112:127]
	ds_read_b128 v[176:179], v231 offset:49152
	ds_read_b128 v[184:187], v231 offset:57344
	ds_read_b128 v[188:191], v232 offset:49152
	ds_read_b128 v[192:195], v232 offset:57344
	v_exp_f32_e32 v94, v94
	v_exp_f32_e32 v95, v95
	s_waitcnt lgkmcnt(4)
	v_mfma_f32_32x32x16_bf16 v[96:111], v[250:253], v[152:155], v[96:111]
	v_add_f32_e32 v196, v65, v64
	v_add_f32_e32 v196, v66, v196
	v_add_f32_e32 v196, v67, v196
	v_add_f32_e32 v196, v68, v196
	v_add_f32_e32 v196, v69, v196
	v_add_f32_e32 v196, v70, v196
	v_add_f32_e32 v196, v71, v196
	v_add_f32_e32 v196, v72, v196
	v_add_f32_e32 v196, v73, v196
	v_add_f32_e32 v196, v74, v196
	v_add_f32_e32 v196, v75, v196
	s_waitcnt lgkmcnt(3)
	v_mfma_f32_32x32x16_bf16 v[112:127], v[176:179], v[148:151], v[112:127]
	v_add_f32_e32 v176, v76, v196
	v_add_f32_e32 v176, v77, v176
	v_add_f32_e32 v176, v78, v176
	v_add_f32_e32 v176, v79, v176
	v_add_f32_e32 v176, v176, v80
	v_add_f32_e32 v176, v81, v176
	v_add_f32_e32 v176, v82, v176
	s_waitcnt lgkmcnt(2)
	v_mfma_f32_32x32x16_bf16 v[96:111], v[184:187], v[148:151], v[96:111]
	v_add_f32_e32 v176, v83, v176
	v_add_f32_e32 v176, v84, v176
	v_add_f32_e32 v176, v85, v176
	v_add_f32_e32 v176, v86, v176
	v_add_f32_e32 v176, v87, v176
	v_add_f32_e32 v176, v88, v176
	v_add_f32_e32 v176, v89, v176
	v_add_f32_e32 v176, v90, v176
	s_waitcnt lgkmcnt(1)
	v_mfma_f32_32x32x16_bf16 v[112:127], v[188:191], v[144:147], v[112:127]
	v_add_f32_e32 v176, v91, v176
	ds_read_b128 v[180:183], v233 offset:49152
	ds_read_b128 v[200:203], v233 offset:57344
	ds_read_b128 v[242:245], v234 offset:49152
	ds_read_b128 v[246:249], v234 offset:57344
	v_add_f32_e32 v176, v92, v176
	v_add_f32_e32 v176, v93, v176
	v_add_f32_e32 v176, v94, v176
	v_add_f32_e32 v196, v95, v176
	s_waitcnt lgkmcnt(4)
	v_mfma_f32_32x32x16_bf16 v[96:111], v[192:195], v[144:147], v[96:111]
	s_waitcnt lgkmcnt(3)
	v_mfma_f32_32x32x16_bf16 v[112:127], v[180:183], v[140:143], v[112:127]
	v_mov_b32_e32 v192, v196
	s_nop 1
	v_permlane32_swap_b32_e32 v196, v192
	v_add_f32_e32 v241, v196, v192
	v_cvt_pk_bf16_f32 v196, v64, v65
	v_cvt_pk_bf16_f32 v197, v66, v67
	s_waitcnt lgkmcnt(2)
	v_mfma_f32_32x32x16_bf16 v[96:111], v[200:203], v[140:143], v[96:111]
	v_cvt_pk_bf16_f32 v198, v68, v69
	v_cvt_pk_bf16_f32 v199, v70, v71
	v_cvt_pk_bf16_f32 v192, v72, v73
	v_cvt_pk_bf16_f32 v193, v74, v75
	v_cvt_pk_bf16_f32 v194, v76, v77
	v_cvt_pk_bf16_f32 v195, v78, v79
	v_fmac_f32_e32 v241, v239, v240
	s_waitcnt lgkmcnt(1)
	v_mfma_f32_32x32x16_bf16 v[112:127], v[242:245], v[136:139], v[112:127]
	ds_read_b128 v[176:179], v230 offset:49152
	ds_read_b128 v[184:187], v230 offset:57344
	ds_read_b128 v[188:191], v235 offset:49152
	ds_read_b128 v[250:253], v235 offset:57344
	v_permlane32_swap_b32_e32 v196, v198
	v_permlane32_swap_b32_e32 v197, v199
	v_permlane32_swap_b32_e32 v192, v194
	v_permlane32_swap_b32_e32 v193, v195
	s_waitcnt lgkmcnt(4)
	v_mfma_f32_32x32x16_bf16 v[96:111], v[246:249], v[136:139], v[96:111]
	s_waitcnt lgkmcnt(3)
	v_mfma_f32_32x32x16_bf16 v[112:127], v[176:179], v[132:135], v[112:127]
	v_cvt_pk_bf16_f32 v200, v80, v81
	v_cvt_pk_bf16_f32 v201, v82, v83
	v_cvt_pk_bf16_f32 v202, v84, v85
	v_cvt_pk_bf16_f32 v203, v86, v87
	v_cvt_pk_bf16_f32 v80, v88, v89
	v_cvt_pk_bf16_f32 v81, v90, v91
	v_cvt_pk_bf16_f32 v82, v92, v93
	s_waitcnt lgkmcnt(2)
	v_mfma_f32_32x32x16_bf16 v[96:111], v[184:187], v[132:135], v[96:111]
	v_cvt_pk_bf16_f32 v83, v94, v95
	v_permlane32_swap_b32_e32 v200, v202
	v_permlane32_swap_b32_e32 v201, v203
	v_permlane32_swap_b32_e32 v80, v82
	s_waitcnt lgkmcnt(1)
	v_mfma_f32_32x32x16_bf16 v[112:127], v[188:191], v[128:131], v[112:127]
	v_permlane32_swap_b32_e32 v81, v83
	s_waitcnt lgkmcnt(0)
	v_mfma_f32_32x32x16_bf16 v[96:111], v[250:253], v[128:131], v[96:111]
	s_waitcnt vmcnt(0)
	s_mov_b32 s11, 0xfff70000
	v_add_co_u32_e32 v84, vcc, s11, v216
	s_mov_b32 s11, 0xfffa0000
	s_nop 0
	v_addc_co_u32_e32 v85, vcc, -1, v217, vcc
	v_add_co_u32_e32 v86, vcc, s11, v216
	s_nop 1
	v_addc_co_u32_e32 v87, vcc, -1, v217, vcc
	global_load_dwordx4 v[176:179], v[84:85], off
	global_load_dwordx4 v[180:183], v[84:85], off offset:-1024
	global_load_dwordx4 v[188:191], v[86:87], off
	global_load_dwordx4 v[184:187], v[86:87], off offset:-1024
	ds_read_b64_tr_b16 v[64:65], v224 offset:0
	ds_read_b64_tr_b16 v[66:67], v224 offset:0x800
	ds_read_b64_tr_b16 v[68:69], v224 offset:0x1000
	ds_read_b64_tr_b16 v[70:71], v224 offset:0x1800
	ds_read_b64_tr_b16 v[72:73], v224 offset:0x2000
	ds_read_b64_tr_b16 v[74:75], v224 offset:0x2800
	ds_read_b64_tr_b16 v[76:77], v224 offset:0x3000
	ds_read_b64_tr_b16 v[78:79], v224 offset:0x3800
	s_waitcnt lgkmcnt(6)
	v_mfma_f32_32x32x16_bf16 v[0:15], v[196:199], v[64:67], v[0:15]
	ds_write_b128 v228, v[168:171] offset:32768
	v_max_f32_e32 v84, v112, v113
	v_max3_f32 v84, v84, v114, v115
	v_max3_f32 v84, v84, v116, v117
	v_max3_f32 v84, v84, v118, v119
	v_max3_f32 v84, v84, v120, v121
	s_waitcnt lgkmcnt(5)
; #define PV_SM(o, vb, a0, a1, a2, a3, q0, q1, m, mn, al) do { if constexpr ((CF::ND0 == 8 || ATT_B_PV) && !MASK) pv_sm<CF>(o, vb, a0, a1, a2, a3, q0, q1, m, mn, al); \
;     else { pv_d0(o, vb, a0, a1, a2, a3); partialSM<CF>(q0, q1, m, mn, al); } } while (0)
; #define PV_SM(o, vb, a0, a1, a2, a3, q0, q1, m, mn, al) do { pv_d0(o, vb, a0, a1, a2, a3); partialSM<CF>(q0, q1, m, mn, al); } while (0)
; #define ATT_SYNC() __syncthreads()
; #define ATT_SWAIT() do { if constexpr (SDEPTH == 2) { if constexpr (ND0 == 12) asm volatile("s_waitcnt vmcnt(5)" ::: "memory"); else asm volatile("s_waitcnt vmcnt(4)" ::: "memory"); } else asm volatile("s_waitcnt vmcnt(0)" ::: "memory"); } while (0)
; template <class CF> __device__ __forceinline__ void pv_sm(f32x16* o, int vb, bf16x8 pa0, bf16x8 pa1, bf16x8 pa2, bf16x8 pa3, f32x16& p0, f32x16& p1, float& m_reg, float& mn, float& alpha) {
;   constexpr float C = CF::SCALE * 1.4426950408889634f;
;   s16x4 f[8];
;   pv_reads<0>(vb, f);
;   float pmax = p0[0];
; #pragma unroll
;   for (int r = 1; r < 16; ++r) pmax = fmaxf(pmax, p0[r]);
;   asm volatile("" : "+v"(pmax));
;   pv_mfma4(o[0], f, pa0, pa1, pa2, pa3);
;   pv_reads<1>(vb, f);
; #pragma unroll
;   for (int r = 0; r < 16; ++r) pmax = fmaxf(pmax, p1[r]);
;   { auto rr = __builtin_amdgcn_permlane32_swap(__float_as_uint(pmax), __float_as_uint(pmax), false, false);
;     pmax = fmaxf(__uint_as_float(rr[0]), __uint_as_float(rr[1])); }
;   asm volatile("" : "+v"(pmax));
;   pv_mfma4(o[1], f, pa0, pa1, pa2, pa3);
;   pv_reads<2>(vb, f);
;   if (__builtin_expect(__all(pmax - m_reg <= THR / CF::SCALE), 1)) { mn = m_reg; alpha = 1.f; }
;   else { mn = fmaxf(m_reg, pmax); alpha = __builtin_amdgcn_exp2f((m_reg - mn) * C); m_reg = mn; }
;   const float mnC = -mn * C;
; #pragma unroll
;   for (int r = 0; r < 16; ++r) p0[r] = fmaf(p0[r], C, mnC);
; #pragma unroll
;   for (int r = 0; r < 16; ++r) p1[r] = fmaf(p1[r], C, mnC);
;   asm volatile("" : "+v"(p0), "+v"(p1));
;   pv_mfma4(o[2], f, pa0, pa1, pa2, pa3);
;   pv_reads<3>(vb, f);
; #pragma unroll
;   for (int r = 0; r < 16; ++r) p0[r] = __builtin_amdgcn_exp2f(p0[r]);
;   asm volatile("" : "+v"(p0));
;   pv_mfma4(o[3], f, pa0, pa1, pa2, pa3);
; }
;     ...
;     PV_SM(o, vb0, pa0, pa1, pa2, pa3, pB0, pB1, m_reg, mnB, alB);
;     ATT_SYNC(); ATT_SWAIT(); ATT_SWRITE(0, SE);
;     ATT_RESC(alB); ATT_SYNC();
	v_mfma_f32_32x32x16_bf16 v[0:15], v[192:195], v[68:71], v[0:15]
	ds_write_b128 v228, v[172:175] offset:40960
	v_max3_f32 v84, v84, v122, v123
	v_max3_f32 v84, v84, v124, v125
	v_max3_f32 v84, v84, v126, v127
	ds_read_b64_tr_b16 v[64:65], v224 offset:0x200
	ds_read_b64_tr_b16 v[66:67], v224 offset:0xa00
	ds_read_b64_tr_b16 v[68:69], v224 offset:0x1200
	s_waitcnt lgkmcnt(7)
	v_mfma_f32_32x32x16_bf16 v[0:15], v[200:203], v[72:75], v[0:15]
	ds_read_b64_tr_b16 v[70:71], v224 offset:0x1a00
	ds_read_b64_tr_b16 v[72:73], v224 offset:0x2200
	ds_read_b64_tr_b16 v[74:75], v224 offset:0x2a00
	s_waitcnt lgkmcnt(8)
	v_mfma_f32_32x32x16_bf16 v[0:15], v[80:83], v[76:79], v[0:15]
	ds_read_b64_tr_b16 v[76:77], v224 offset:0x3200
	ds_read_b64_tr_b16 v[78:79], v224 offset:0x3a00
	s_waitcnt lgkmcnt(6)
	v_mfma_f32_32x32x16_bf16 v[48:63], v[196:199], v[64:67], v[48:63]
	v_max3_f32 v84, v84, v96, v97
	v_max3_f32 v84, v84, v98, v99
	v_max3_f32 v84, v84, v100, v101
	v_max3_f32 v84, v84, v102, v103
	v_max3_f32 v84, v84, v104, v105
	v_max3_f32 v84, v84, v106, v107
	v_max3_f32 v84, v84, v108, v109
	s_waitcnt lgkmcnt(4)
	v_mfma_f32_32x32x16_bf16 v[48:63], v[192:195], v[68:71], v[48:63]
	v_max3_f32 v84, v84, v110, v111
	v_mov_b32_e32 v85, v84
	s_nop 1
	v_permlane32_swap_b32_e32 v84, v85
	v_max_f32_e32 v92, v84, v85
	s_waitcnt lgkmcnt(2)
	v_mfma_f32_32x32x16_bf16 v[48:63], v[200:203], v[72:75], v[48:63]
	ds_read_b64_tr_b16 v[64:65], v224 offset:0x400
	ds_read_b64_tr_b16 v[66:67], v224 offset:0xc00
	ds_read_b64_tr_b16 v[68:69], v224 offset:0x1400
	ds_read_b64_tr_b16 v[70:71], v224 offset:0x1c00
	ds_read_b64_tr_b16 v[84:85], v224 offset:0x2400
	ds_read_b64_tr_b16 v[86:87], v224 offset:0x2c00
	s_waitcnt lgkmcnt(6)
	v_mfma_f32_32x32x16_bf16 v[48:63], v[80:83], v[76:79], v[48:63]
	ds_read_b64_tr_b16 v[88:89], v224 offset:0x3400
	ds_read_b64_tr_b16 v[90:91], v224 offset:0x3c00
	s_waitcnt lgkmcnt(6)
	v_mfma_f32_32x32x16_bf16 v[32:47], v[196:199], v[64:67], v[32:47]
	v_sub_f32_e32 v72, v92, v238
	v_cmp_ge_f32_e32 vcc, s66, v72
	v_max_f32_e32 v72, v238, v92
	v_sub_f32_e32 v73, v238, v72
	v_mul_f32_e32 v73, 0x3e0293ee, v73
	s_waitcnt lgkmcnt(4)
	v_mfma_f32_32x32x16_bf16 v[32:47], v[192:195], v[68:71], v[32:47]
	ds_read_b64_tr_b16 v[206:207], v224 offset:0x600
	ds_read_b64_tr_b16 v[208:209], v224 offset:0xe00
	ds_read_b64_tr_b16 v[210:211], v224 offset:0x1600
	ds_read_b64_tr_b16 v[212:213], v224 offset:0x1e00
	s_cmp_eq_u64 vcc, exec
	v_exp_f32_e32 v73, v73
	s_cselect_b64 vcc, -1, 0
	v_cndmask_b32_e32 v238, v72, v238, vcc
	v_mul_f32_e32 v92, 0xbe0293ee, v238
	v_cndmask_b32_e64 v239, v73, 1.0, vcc
	v_pk_fma_f32 v[78:79], v[126:127], s[74:75], v[92:93] op_sel_hi:[1,0,0]
	s_waitcnt lgkmcnt(6)
	v_mfma_f32_32x32x16_bf16 v[32:47], v[200:203], v[84:87], v[32:47]
	ds_read_b64_tr_b16 v[218:219], v224 offset:0x2600
	ds_read_b64_tr_b16 v[220:221], v224 offset:0x2e00
	ds_read_b64_tr_b16 v[246:247], v224 offset:0x3600
	ds_read_b64_tr_b16 v[248:249], v224 offset:0x3e00
	v_fma_f32 v76, v124, s74, v92
	v_fma_f32 v77, v125, s74, v92
	v_fma_f32 v74, v122, s74, v92
	v_fma_f32 v75, v123, s74, v92
	v_fma_f32 v72, v120, s74, v92
	v_fma_f32 v73, v121, s74, v92
	v_pk_fma_f32 v[70:71], v[118:119], s[74:75], v[92:93] op_sel_hi:[1,0,0]
	v_pk_fma_f32 v[68:69], v[116:117], s[74:75], v[92:93] op_sel_hi:[1,0,0]
	v_pk_fma_f32 v[66:67], v[114:115], s[74:75], v[92:93] op_sel_hi:[1,0,0]
	v_pk_fma_f32 v[64:65], v[112:113], s[74:75], v[92:93] op_sel_hi:[1,0,0]
	v_pk_fma_f32 v[126:127], v[110:111], s[74:75], v[92:93] op_sel_hi:[1,0,0]
	v_pk_fma_f32 v[124:125], v[108:109], s[74:75], v[92:93] op_sel_hi:[1,0,0]
	v_pk_fma_f32 v[122:123], v[106:107], s[74:75], v[92:93] op_sel_hi:[1,0,0]
	v_pk_fma_f32 v[120:121], v[104:105], s[74:75], v[92:93] op_sel_hi:[1,0,0]
	v_pk_fma_f32 v[118:119], v[102:103], s[74:75], v[92:93] op_sel_hi:[1,0,0]
	v_pk_fma_f32 v[116:117], v[100:101], s[74:75], v[92:93] op_sel_hi:[1,0,0]
	v_pk_fma_f32 v[114:115], v[98:99], s[74:75], v[92:93] op_sel_hi:[1,0,0]
	v_pk_fma_f32 v[112:113], v[96:97], s[74:75], v[92:93] op_sel_hi:[1,0,0]
	s_waitcnt lgkmcnt(8)
	v_mfma_f32_32x32x16_bf16 v[32:47], v[80:83], v[88:91], v[32:47]
	s_waitcnt lgkmcnt(0)
	s_barrier
	v_mfma_f32_32x32x16_bf16 v[16:31], v[196:199], v[206:209], v[16:31]
	ds_write_b128 v226, v[160:163]
	v_exp_f32_e32 v96, v64
	v_exp_f32_e32 v97, v65
	v_exp_f32_e32 v98, v66
	v_exp_f32_e32 v99, v67
	v_exp_f32_e32 v100, v68
	v_exp_f32_e32 v101, v69
	v_exp_f32_e32 v102, v70
	v_mfma_f32_32x32x16_bf16 v[16:31], v[192:195], v[210:213], v[16:31]
	ds_write_b128 v227, v[164:167]
	v_exp_f32_e32 v103, v71
	v_exp_f32_e32 v104, v72
	v_exp_f32_e32 v105, v73
	v_exp_f32_e32 v106, v74
	v_exp_f32_e32 v107, v75
	v_exp_f32_e32 v108, v76
	v_exp_f32_e32 v109, v77
	v_mfma_f32_32x32x16_bf16 v[16:31], v[200:203], v[218:221], v[16:31]
	v_exp_f32_e32 v110, v78
	v_exp_f32_e32 v111, v79
	v_mfma_f32_32x32x16_bf16 v[16:31], v[80:83], v[246:249], v[16:31]
	v_cmp_gt_f32_e32 vcc, 1.0, v239
	s_cbranch_vccz .LBB0_807
	s_and_saveexec_b64 s[12:13], s[4:5]
	ds_write_b32 v237, v239 offset:128
	s_or_b64 exec, exec, s[12:13]
	s_waitcnt lgkmcnt(0)
	v_add_u32_e32 v76, v223, v204
	ds_read_b128 v[64:67], v76 offset:224
	ds_read_b128 v[68:71], v76 offset:192
	ds_read_b128 v[72:75], v76 offset:160
	ds_read_b128 v[76:79], v76 offset:128
	s_waitcnt lgkmcnt(3)
	v_pk_mul_f32 v[12:13], v[12:13], v[64:65]
	s_waitcnt lgkmcnt(2)
	v_pk_mul_f32 v[8:9], v[8:9], v[68:69]
	s_waitcnt lgkmcnt(1)
	v_pk_mul_f32 v[4:5], v[4:5], v[72:73]
	v_pk_mul_f32 v[14:15], v[14:15], v[66:67]
	v_pk_mul_f32 v[10:11], v[10:11], v[70:71]
	v_pk_mul_f32 v[6:7], v[6:7], v[74:75]
	s_waitcnt lgkmcnt(0)
	v_pk_mul_f32 v[2:3], v[2:3], v[78:79]
	v_pk_mul_f32 v[0:1], v[0:1], v[76:77]
	v_pk_mul_f32 v[60:61], v[60:61], v[64:65]
	v_pk_mul_f32 v[56:57], v[56:57], v[68:69]
	v_pk_mul_f32 v[52:53], v[52:53], v[72:73]
	v_pk_mul_f32 v[62:63], v[62:63], v[66:67]
	v_pk_mul_f32 v[58:59], v[58:59], v[70:71]
	v_pk_mul_f32 v[54:55], v[54:55], v[74:75]
	v_pk_mul_f32 v[50:51], v[50:51], v[78:79]
	v_pk_mul_f32 v[48:49], v[48:49], v[76:77]
	v_pk_mul_f32 v[44:45], v[44:45], v[64:65]
	v_pk_mul_f32 v[40:41], v[40:41], v[68:69]
	v_pk_mul_f32 v[36:37], v[36:37], v[72:73]
	v_pk_mul_f32 v[46:47], v[46:47], v[66:67]
	v_pk_mul_f32 v[42:43], v[42:43], v[70:71]
	v_pk_mul_f32 v[38:39], v[38:39], v[74:75]
	v_pk_mul_f32 v[34:35], v[34:35], v[78:79]
	v_pk_mul_f32 v[32:33], v[32:33], v[76:77]
	v_pk_mul_f32 v[28:29], v[28:29], v[64:65]
	v_pk_mul_f32 v[24:25], v[24:25], v[68:69]
	v_pk_mul_f32 v[20:21], v[20:21], v[72:73]
	v_pk_mul_f32 v[30:31], v[30:31], v[66:67]
	v_pk_mul_f32 v[26:27], v[26:27], v[70:71]
	v_pk_mul_f32 v[22:23], v[22:23], v[74:75]
	v_pk_mul_f32 v[18:19], v[18:19], v[78:79]
	v_pk_mul_f32 v[16:17], v[16:17], v[76:77]
; #define ATT_SBAR() __builtin_amdgcn_sched_barrier(0)
; #define ATT_QRD(dst, g) do { _Pragma("unroll") for (int t = 0; t < 2; ++t) { const int cb = ((2 * (g) + t) * 16 + hi * 8) * 2; \
;     dst[2 * t] = *reinterpret_cast<const bf16x8*>(kr + (cb ^ sw)); dst[2 * t + 1] = *reinterpret_cast<const bf16x8*>(kr + 32 * CF::KPITCH + (cb ^ sw)); } } while (0)
; #define ATT_QEARLY(dst, g) do { } while (0)
; #define ATT_QEARLY(dst, g) ATT_QRD(dst, g)
; template <class CF> __device__ __forceinline__ void qk_sm(f32x16& n0, f32x16& n1, const char* Ks, const bf16x8* qr, int r32, int hi,
;                                                           f32x16& p0, f32x16& p1, float alpha, float& l_reg, bf16x8& pa0, bf16x8& pa1, bf16x8& pa2, bf16x8& pa3) {
;   n0 = f32x16{}; n1 = f32x16{};
;   const char* kr = Ks + r32 * CF::KPITCH; const int sw = (r32 & CF::KSWM) << 4;
;   bf16x8 ka[4], kb[4];
;     ...
;   ATT_QRD(ka, 0); ATT_QRD(kb, 1); asm volatile("s_waitcnt lgkmcnt(4)" ::: "memory"); ATT_SBAR();
;     ...
;   ATT_QRD(ka, 0); asm volatile("s_waitcnt lgkmcnt(0)" ::: "memory"); ATT_SBAR();
;     ...
;   ATT_QEARLY(kb, 1);
; #pragma unroll
;   for (int r = 0; r < 16; ++r) p1[r] = __builtin_amdgcn_exp2f(p1[r]);
;   asm volatile("" : "+v"(p1));
;   ATT_QMM(ka, 0);
;     ...
;   ATT_QRD(ka, 2); asm volatile("s_waitcnt lgkmcnt(4)" ::: "memory"); ATT_SBAR();
;     ...
;   asm volatile("s_waitcnt lgkmcnt(0)" ::: "memory"); ATT_SBAR();
;     ...
;   ATT_QEARLY(ka, 2);
;   float ps = 0;
; #pragma unroll
;   for (int r = 0; r < 16; ++r) ps += p0[r];
; #pragma unroll
;   for (int r = 0; r < 16; ++r) ps += p1[r];
;   asm volatile("" : "+v"(ps));
;   ATT_QMM(kb, 1);
;     ...
;   ATT_QRD(kb, 3); asm volatile("s_waitcnt lgkmcnt(4)" ::: "memory"); ATT_SBAR();
;     ...
;   asm volatile("s_waitcnt lgkmcnt(0)" ::: "memory"); ATT_SBAR();
;     ...
;   ATT_QEARLY(kb, 3);
;   { auto rr = __builtin_amdgcn_permlane32_swap(__float_as_uint(ps), __float_as_uint(ps), false, false);
;     ps = __uint_as_float(rr[0]) + __uint_as_float(rr[1]); }
;   l_reg = l_reg * alpha + ps;
;   ATT_PK4(p0, 0, pa0); ATT_PK4(p0, 8, pa1);
;   asm volatile("" : "+v"(l_reg), "+v"(pa0), "+v"(pa1));
;   ATT_QMM(ka, 2);
;   asm volatile("s_waitcnt lgkmcnt(0)" ::: "memory"); ATT_SBAR();
;   ATT_PK4(p1, 0, pa2); ATT_PK4(p1, 8, pa3);
;   asm volatile("" : "+v"(pa2), "+v"(pa3));
;   ATT_QMM(kb, 3);
;     ...
;     if (SDEPTH == 1 || j + 3 < NT) ATT_SLOAD(SE, (j + 1 + SDEPTH) * KVBLK); ATT_SBAR();
.LBB0_807:
	ds_read_b128 v[206:209], v229 offset:32768
	ds_read_b128 v[210:213], v229 offset:40960
	ds_read_b128 v[218:221], v236 offset:32768
	ds_read_b128 v[250:253], v236 offset:40960
	s_waitcnt lgkmcnt(3)
	v_mfma_f32_32x32x16_bf16 v[80:95], v[206:209], v[156:159], 0
	v_exp_f32_e32 v112, v112
	v_exp_f32_e32 v113, v113
	v_exp_f32_e32 v114, v114
	v_exp_f32_e32 v115, v115
	v_exp_f32_e32 v116, v116
	v_exp_f32_e32 v117, v117
	v_exp_f32_e32 v118, v118
	s_waitcnt lgkmcnt(2)
	v_mfma_f32_32x32x16_bf16 v[64:79], v[210:213], v[156:159], 0
	v_exp_f32_e32 v119, v119
	v_exp_f32_e32 v120, v120
	v_exp_f32_e32 v121, v121
	v_exp_f32_e32 v122, v122
	v_exp_f32_e32 v123, v123
	v_exp_f32_e32 v124, v124
	v_exp_f32_e32 v125, v125
	s_waitcnt lgkmcnt(1)
	v_mfma_f32_32x32x16_bf16 v[80:95], v[218:221], v[152:155], v[80:95]
	ds_read_b128 v[192:195], v231 offset:32768
	ds_read_b128 v[200:203], v231 offset:40960
	ds_read_b128 v[242:245], v232 offset:32768
	ds_read_b128 v[246:249], v232 offset:40960
	v_exp_f32_e32 v126, v126
	v_exp_f32_e32 v127, v127
	s_waitcnt lgkmcnt(4)
	v_mfma_f32_32x32x16_bf16 v[64:79], v[250:253], v[152:155], v[64:79]
	v_add_f32_e32 v218, v97, v96
	v_add_f32_e32 v218, v98, v218
	v_add_f32_e32 v218, v99, v218
	v_add_f32_e32 v218, v100, v218
	v_add_f32_e32 v218, v101, v218
	v_add_f32_e32 v218, v102, v218
	v_add_f32_e32 v218, v103, v218
	v_add_f32_e32 v218, v104, v218
	v_add_f32_e32 v218, v105, v218
	v_add_f32_e32 v218, v106, v218
	v_add_f32_e32 v218, v107, v218
	s_waitcnt lgkmcnt(3)
	v_mfma_f32_32x32x16_bf16 v[80:95], v[192:195], v[148:151], v[80:95]
	v_add_f32_e32 v192, v108, v218
	v_add_f32_e32 v192, v109, v192
	v_add_f32_e32 v192, v110, v192
	v_add_f32_e32 v192, v111, v192
	v_add_f32_e32 v192, v192, v112
	v_add_f32_e32 v192, v113, v192
	v_add_f32_e32 v192, v114, v192
	s_waitcnt lgkmcnt(2)
	v_mfma_f32_32x32x16_bf16 v[64:79], v[200:203], v[148:151], v[64:79]
	v_add_f32_e32 v192, v115, v192
	v_add_f32_e32 v192, v116, v192
	v_add_f32_e32 v192, v117, v192
	v_add_f32_e32 v192, v118, v192
	v_add_f32_e32 v192, v119, v192
	v_add_f32_e32 v192, v120, v192
	v_add_f32_e32 v192, v121, v192
	v_add_f32_e32 v192, v122, v192
	s_waitcnt lgkmcnt(1)
	v_mfma_f32_32x32x16_bf16 v[80:95], v[242:245], v[144:147], v[80:95]
	v_add_f32_e32 v192, v123, v192
	ds_read_b128 v[196:199], v233 offset:32768
	ds_read_b128 v[250:253], v233 offset:40960
	ds_read_b128 v[210:213], v234 offset:32768
	ds_read_b128 v[206:209], v234 offset:40960
	v_add_f32_e32 v192, v124, v192
	v_add_f32_e32 v192, v125, v192
	v_add_f32_e32 v192, v126, v192
	v_add_f32_e32 v192, v127, v192
	s_waitcnt lgkmcnt(4)
	v_mfma_f32_32x32x16_bf16 v[64:79], v[246:249], v[144:147], v[64:79]
	s_waitcnt lgkmcnt(3)
	v_mfma_f32_32x32x16_bf16 v[80:95], v[196:199], v[140:143], v[80:95]
	v_mov_b32_e32 v193, v192
	s_nop 1
	v_permlane32_swap_b32_e32 v192, v193
	v_add_f32_e32 v240, v192, v193
	v_cvt_pk_bf16_f32 v196, v96, v97
	v_cvt_pk_bf16_f32 v197, v98, v99
	s_waitcnt lgkmcnt(2)
	v_mfma_f32_32x32x16_bf16 v[64:79], v[250:253], v[140:143], v[64:79]
	v_cvt_pk_bf16_f32 v198, v100, v101
	v_cvt_pk_bf16_f32 v199, v102, v103
	v_cvt_pk_bf16_f32 v192, v104, v105
	v_cvt_pk_bf16_f32 v193, v106, v107
	v_cvt_pk_bf16_f32 v194, v108, v109
	v_cvt_pk_bf16_f32 v195, v110, v111
	v_fmac_f32_e32 v240, v241, v239
	s_waitcnt lgkmcnt(1)
	v_mfma_f32_32x32x16_bf16 v[80:95], v[210:213], v[136:139], v[80:95]
	ds_read_b128 v[200:203], v230 offset:32768
	ds_read_b128 v[242:245], v230 offset:40960
	ds_read_b128 v[246:249], v235 offset:32768
	ds_read_b128 v[218:221], v235 offset:40960
	v_permlane32_swap_b32_e32 v196, v198
	v_permlane32_swap_b32_e32 v197, v199
	v_permlane32_swap_b32_e32 v192, v194
	v_permlane32_swap_b32_e32 v193, v195
	s_waitcnt lgkmcnt(4)
	v_mfma_f32_32x32x16_bf16 v[64:79], v[206:209], v[136:139], v[64:79]
	s_waitcnt lgkmcnt(3)
	v_mfma_f32_32x32x16_bf16 v[80:95], v[200:203], v[132:135], v[80:95]
	v_cvt_pk_bf16_f32 v200, v112, v113
	v_cvt_pk_bf16_f32 v201, v114, v115
	v_cvt_pk_bf16_f32 v202, v116, v117
	v_cvt_pk_bf16_f32 v203, v118, v119
	v_cvt_pk_bf16_f32 v112, v120, v121
	v_cvt_pk_bf16_f32 v113, v122, v123
	v_cvt_pk_bf16_f32 v114, v124, v125
	s_waitcnt lgkmcnt(2)
	v_mfma_f32_32x32x16_bf16 v[64:79], v[242:245], v[132:135], v[64:79]
	v_cvt_pk_bf16_f32 v115, v126, v127
	v_permlane32_swap_b32_e32 v200, v202
	v_permlane32_swap_b32_e32 v201, v203
	v_permlane32_swap_b32_e32 v112, v114
	s_waitcnt lgkmcnt(1)
	v_mfma_f32_32x32x16_bf16 v[80:95], v[246:249], v[128:131], v[80:95]
	v_permlane32_swap_b32_e32 v113, v115
	s_waitcnt lgkmcnt(0)
	v_mfma_f32_32x32x16_bf16 v[64:79], v[218:221], v[128:131], v[64:79]
	s_waitcnt vmcnt(0)
	s_add_i32 s10, s10, 2
	s_cmp_ge_u32 s10, s0
	s_cselect_b64 s[12:13], -1, 0
	s_and_b64 vcc, exec, s[12:13]
	s_cbranch_vccnz .LBB0_809
	v_add_co_u32_e32 v116, vcc, 0xfffd0000, v216
	s_nop 1
	v_addc_co_u32_e32 v117, vcc, -1, v217, vcc
	global_load_dwordx4 v[160:163], v[116:117], off
	global_load_dwordx4 v[168:171], v[116:117], off offset:-1024
	global_load_dwordx4 v[164:167], v[216:217], off
	global_load_dwordx4 v[172:175], v[216:217], off offset:-1024
; template <class CF> __device__ __forceinline__ void pv_sm(f32x16* o, int vb, bf16x8 pa0, bf16x8 pa1, bf16x8 pa2, bf16x8 pa3, f32x16& p0, f32x16& p1, float& m_reg, float& mn, float& alpha) {
;   constexpr float C = CF::SCALE * 1.4426950408889634f;
;   s16x4 f[8];
;   pv_reads<0>(vb, f);
;   float pmax = p0[0];
; #pragma unroll
;   for (int r = 1; r < 16; ++r) pmax = fmaxf(pmax, p0[r]);
;   asm volatile("" : "+v"(pmax));
;   pv_mfma4(o[0], f, pa0, pa1, pa2, pa3);
;   pv_reads<1>(vb, f);
; #pragma unroll
;   for (int r = 0; r < 16; ++r) pmax = fmaxf(pmax, p1[r]);
;   { auto rr = __builtin_amdgcn_permlane32_swap(__float_as_uint(pmax), __float_as_uint(pmax), false, false);
;     pmax = fmaxf(__uint_as_float(rr[0]), __uint_as_float(rr[1])); }
;   asm volatile("" : "+v"(pmax));
;   pv_mfma4(o[1], f, pa0, pa1, pa2, pa3);
;   pv_reads<2>(vb, f);
;   if (__builtin_expect(__all(pmax - m_reg <= THR / CF::SCALE), 1)) { mn = m_reg; alpha = 1.f; }
;   else { mn = fmaxf(m_reg, pmax); alpha = __builtin_amdgcn_exp2f((m_reg - mn) * C); m_reg = mn; }
;   const float mnC = -mn * C;
; #pragma unroll
;   for (int r = 0; r < 16; ++r) p0[r] = fmaf(p0[r], C, mnC);
; #pragma unroll
;   for (int r = 0; r < 16; ++r) p1[r] = fmaf(p1[r], C, mnC);
;   asm volatile("" : "+v"(p0), "+v"(p1));
;   pv_mfma4(o[2], f, pa0, pa1, pa2, pa3);
;   pv_reads<3>(vb, f);
; #pragma unroll
;   for (int r = 0; r < 16; ++r) p0[r] = __builtin_amdgcn_exp2f(p0[r]);
;   asm volatile("" : "+v"(p0));
;   pv_mfma4(o[3], f, pa0, pa1, pa2, pa3);
.LBB0_809:
	ds_read_b64_tr_b16 v[96:97], v225 offset:0
	ds_read_b64_tr_b16 v[98:99], v225 offset:0x800
	ds_read_b64_tr_b16 v[100:101], v225 offset:0x1000
	ds_read_b64_tr_b16 v[102:103], v225 offset:0x1800
	ds_read_b64_tr_b16 v[104:105], v225 offset:0x2000
	ds_read_b64_tr_b16 v[106:107], v225 offset:0x2800
	ds_read_b64_tr_b16 v[108:109], v225 offset:0x3000
	ds_read_b64_tr_b16 v[110:111], v225 offset:0x3800
	s_waitcnt lgkmcnt(6)
	v_mfma_f32_32x32x16_bf16 v[0:15], v[196:199], v[96:99], v[0:15]
	ds_write_b128 v228, v[180:183] offset:49152
	s_nop 1
	v_max_f32_e32 v116, v80, v81
	v_max3_f32 v116, v116, v82, v83
	v_max3_f32 v116, v116, v84, v85
	v_max3_f32 v116, v116, v86, v87
	v_max3_f32 v116, v116, v88, v89
	s_waitcnt lgkmcnt(5)
	v_mfma_f32_32x32x16_bf16 v[0:15], v[192:195], v[100:103], v[0:15]
	ds_write_b128 v228, v[184:187] offset:57344
	v_max3_f32 v116, v116, v90, v91
	v_max3_f32 v116, v116, v92, v93
	v_max3_f32 v116, v116, v94, v95
	ds_read_b64_tr_b16 v[96:97], v225 offset:0x200
	ds_read_b64_tr_b16 v[98:99], v225 offset:0xa00
	ds_read_b64_tr_b16 v[100:101], v225 offset:0x1200
	s_waitcnt lgkmcnt(7)
	v_mfma_f32_32x32x16_bf16 v[0:15], v[200:203], v[104:107], v[0:15]
	ds_read_b64_tr_b16 v[102:103], v225 offset:0x1a00
	ds_read_b64_tr_b16 v[104:105], v225 offset:0x2200
	ds_read_b64_tr_b16 v[106:107], v225 offset:0x2a00
	s_waitcnt lgkmcnt(8)
	v_mfma_f32_32x32x16_bf16 v[0:15], v[112:115], v[108:111], v[0:15]
	ds_read_b64_tr_b16 v[108:109], v225 offset:0x3200
	ds_read_b64_tr_b16 v[110:111], v225 offset:0x3a00
	s_waitcnt lgkmcnt(6)
	v_mfma_f32_32x32x16_bf16 v[48:63], v[196:199], v[96:99], v[48:63]
	v_max3_f32 v116, v116, v64, v65
	v_max3_f32 v116, v116, v66, v67
	v_max3_f32 v116, v116, v68, v69
	v_max3_f32 v116, v116, v70, v71
	v_max3_f32 v116, v116, v72, v73
	v_max3_f32 v116, v116, v74, v75
	v_max3_f32 v116, v116, v76, v77
	s_waitcnt lgkmcnt(4)
	v_mfma_f32_32x32x16_bf16 v[48:63], v[192:195], v[100:103], v[48:63]
	v_max3_f32 v116, v116, v78, v79
	v_mov_b32_e32 v117, v116
	s_nop 1
	v_permlane32_swap_b32_e32 v116, v117
	v_max_f32_e32 v124, v116, v117
	s_waitcnt lgkmcnt(2)
	v_mfma_f32_32x32x16_bf16 v[48:63], v[200:203], v[104:107], v[48:63]
	ds_read_b64_tr_b16 v[96:97], v225 offset:0x400
	ds_read_b64_tr_b16 v[98:99], v225 offset:0xc00
	ds_read_b64_tr_b16 v[100:101], v225 offset:0x1400
	ds_read_b64_tr_b16 v[102:103], v225 offset:0x1c00
	ds_read_b64_tr_b16 v[116:117], v225 offset:0x2400
	ds_read_b64_tr_b16 v[118:119], v225 offset:0x2c00
	s_waitcnt lgkmcnt(6)
	v_mfma_f32_32x32x16_bf16 v[48:63], v[112:115], v[108:111], v[48:63]
	ds_read_b64_tr_b16 v[120:121], v225 offset:0x3400
	ds_read_b64_tr_b16 v[122:123], v225 offset:0x3c00
	s_waitcnt lgkmcnt(6)
	v_mfma_f32_32x32x16_bf16 v[32:47], v[196:199], v[96:99], v[32:47]
	v_sub_f32_e32 v104, v124, v238
	v_cmp_ge_f32_e32 vcc, s66, v104
	v_max_f32_e32 v104, v238, v124
	v_sub_f32_e32 v105, v238, v104
	v_mul_f32_e32 v105, 0x3e0293ee, v105
	s_waitcnt lgkmcnt(4)
	v_mfma_f32_32x32x16_bf16 v[32:47], v[192:195], v[100:103], v[32:47]
	ds_read_b64_tr_b16 v[206:207], v225 offset:0x600
	ds_read_b64_tr_b16 v[208:209], v225 offset:0xe00
	ds_read_b64_tr_b16 v[210:211], v225 offset:0x1600
	ds_read_b64_tr_b16 v[212:213], v225 offset:0x1e00
	s_cmp_eq_u64 vcc, exec
	v_exp_f32_e32 v105, v105
	s_cselect_b64 vcc, -1, 0
	v_cndmask_b32_e32 v238, v104, v238, vcc
	v_mul_f32_e32 v124, 0xbe0293ee, v238
	v_cndmask_b32_e64 v239, v105, 1.0, vcc
	v_pk_fma_f32 v[110:111], v[94:95], s[74:75], v[124:125] op_sel_hi:[1,0,0]
	s_waitcnt lgkmcnt(6)
	v_mfma_f32_32x32x16_bf16 v[32:47], v[200:203], v[116:119], v[32:47]
	ds_read_b64_tr_b16 v[218:219], v225 offset:0x2600
	ds_read_b64_tr_b16 v[220:221], v225 offset:0x2e00
	ds_read_b64_tr_b16 v[246:247], v225 offset:0x3600
	ds_read_b64_tr_b16 v[248:249], v225 offset:0x3e00
	v_fma_f32 v108, v92, s74, v124
	v_fma_f32 v109, v93, s74, v124
	v_fma_f32 v106, v90, s74, v124
	v_fma_f32 v107, v91, s74, v124
	v_fma_f32 v104, v88, s74, v124
	v_fma_f32 v105, v89, s74, v124
	v_pk_fma_f32 v[102:103], v[86:87], s[74:75], v[124:125] op_sel_hi:[1,0,0]
	v_pk_fma_f32 v[100:101], v[84:85], s[74:75], v[124:125] op_sel_hi:[1,0,0]
	v_pk_fma_f32 v[98:99], v[82:83], s[74:75], v[124:125] op_sel_hi:[1,0,0]
	v_pk_fma_f32 v[96:97], v[80:81], s[74:75], v[124:125] op_sel_hi:[1,0,0]
	v_pk_fma_f32 v[94:95], v[78:79], s[74:75], v[124:125] op_sel_hi:[1,0,0]
	v_pk_fma_f32 v[92:93], v[76:77], s[74:75], v[124:125] op_sel_hi:[1,0,0]
	v_pk_fma_f32 v[90:91], v[74:75], s[74:75], v[124:125] op_sel_hi:[1,0,0]
	v_pk_fma_f32 v[88:89], v[72:73], s[74:75], v[124:125] op_sel_hi:[1,0,0]
	v_pk_fma_f32 v[86:87], v[70:71], s[74:75], v[124:125] op_sel_hi:[1,0,0]
	v_pk_fma_f32 v[84:85], v[68:69], s[74:75], v[124:125] op_sel_hi:[1,0,0]
	v_pk_fma_f32 v[82:83], v[66:67], s[74:75], v[124:125] op_sel_hi:[1,0,0]
	v_pk_fma_f32 v[80:81], v[64:65], s[74:75], v[124:125] op_sel_hi:[1,0,0]
	s_waitcnt lgkmcnt(8)
	v_mfma_f32_32x32x16_bf16 v[32:47], v[112:115], v[120:123], v[32:47]
	s_waitcnt lgkmcnt(0)
	s_barrier
	v_mfma_f32_32x32x16_bf16 v[16:31], v[196:199], v[206:209], v[16:31]
	ds_write_b128 v226, v[176:179] offset:16384
	v_exp_f32_e32 v64, v96
	v_exp_f32_e32 v65, v97
	v_exp_f32_e32 v66, v98
	v_exp_f32_e32 v67, v99
	v_exp_f32_e32 v68, v100
	v_exp_f32_e32 v69, v101
	v_exp_f32_e32 v70, v102
	v_mfma_f32_32x32x16_bf16 v[16:31], v[192:195], v[210:213], v[16:31]
	ds_write_b128 v227, v[188:191] offset:16384
	v_exp_f32_e32 v71, v103
	v_exp_f32_e32 v72, v104
	v_exp_f32_e32 v73, v105
	v_exp_f32_e32 v74, v106
	v_exp_f32_e32 v75, v107
	v_exp_f32_e32 v76, v108
	v_exp_f32_e32 v77, v109
	v_mfma_f32_32x32x16_bf16 v[16:31], v[200:203], v[218:221], v[16:31]
	v_exp_f32_e32 v78, v110
	v_exp_f32_e32 v79, v111
	v_mfma_f32_32x32x16_bf16 v[16:31], v[112:115], v[246:249], v[16:31]
	v_cmp_gt_f32_e32 vcc, 1.0, v239
	s_cbranch_vccz .LBB0_802
	s_and_saveexec_b64 s[14:15], s[4:5]
	s_cbranch_execz .LBB0_801
	ds_write_b32 v237, v239 offset:128
	s_branch .LBB0_801

; #define ATT_SBAR() __builtin_amdgcn_sched_barrier(0)
; #define ATT_QRD(dst, g) do { _Pragma("unroll") for (int t = 0; t < 2; ++t) { const int cb = ((2 * (g) + t) * 16 + hi * 8) * 2; \
;     dst[2 * t] = *reinterpret_cast<const bf16x8*>(kr + (cb ^ sw)); dst[2 * t + 1] = *reinterpret_cast<const bf16x8*>(kr + 32 * CF::KPITCH + (cb ^ sw)); } } while (0)
; #define ATT_QRD(b, d0) do { const int cb = ((d0) * 16 + hi * 8) * 2; kf[b][0] = *reinterpret_cast<const bf16x8*>(kr + (cb ^ sw)); kf[b][1] = *reinterpret_cast<const bf16x8*>(kr + 32 * CF::KPITCH + (cb ^ sw)); \
;     if ((d0) >= CF::NQR) qf[b] = *reinterpret_cast<const bf16x8*>(qx + ((d0) - CF::NQR) * 1024); } while (0)
; template <class CF> __device__ __forceinline__ void qk_sm1(f32x16& n0, f32x16& n1, const char* Ks, const bf16x8* qr, const char* qx, int r32, int hi, ...
;   static_assert(CF::ND0 == 12, "qk_sm1: 12 d0 steps");
;   n0 = f32x16{}; n1 = f32x16{};
;   const char* kr = Ks + r32 * CF::KPITCH; const int sw = (r32 & CF::KSWM) << 4;
;   bf16x8 kf[2][2], qf[2];
;     ...
;   ATT_QRD(0, 0); asm volatile("s_waitcnt lgkmcnt(0)" ::: "memory"); ATT_SBAR();
;   float ps = 0;
; #pragma unroll
;   for (int g = 0; g < 12; ++g) {
;     if (g + 1 < 12) ATT_QRD((g + 1) & 1, g + 1);
;     if (g < 2) {
; #pragma unroll
;       for (int r = 0; r < 8; ++r) p1[8 * g + r] = __builtin_amdgcn_exp2f(p1[8 * g + r]);
;       if (g == 1) asm volatile("" : "+v"(p1)); }
;     else if (g < 6) {
; #pragma unroll
;       for (int r = 0; r < 8; ++r) ps += (g < 4 ? p0[8 * (g - 2) + r] : p1[8 * (g - 4) + r]);
;       asm volatile("" : "+v"(ps)); }
;     else if (g == 6) {
;       { auto rr = __builtin_amdgcn_permlane32_swap(__float_as_uint(ps), __float_as_uint(ps), false, false);
;         ps = __uint_as_float(rr[0]) + __uint_as_float(rr[1]); }
.LBB0_1725:
	v_add_u32_e32 v237, v200, v236
	v_add_u32_e32 v238, v235, v236
	ds_read_b128 v[96:99], v237 offset:57344
	ds_read_b128 v[100:103], v238 offset:12288
	s_waitcnt lgkmcnt(1)
	v_mfma_f32_32x32x16_bf16 v[112:127], v[96:99], v[148:151], 0
	v_add_u32_e32 v239, v235, v216
	ds_read_b128 v[152:155], v215 offset:57344
	ds_read_b128 v[156:159], v239 offset:12288
	v_exp_f32_e32 v80, v80
	v_exp_f32_e32 v81, v81
	v_exp_f32_e32 v82, v82
	v_exp_f32_e32 v83, v83
	s_waitcnt lgkmcnt(2)
	v_mfma_f32_32x32x16_bf16 v[96:111], v[100:103], v[148:151], 0
	v_exp_f32_e32 v84, v84
	v_exp_f32_e32 v85, v85
	v_exp_f32_e32 v86, v86
	v_exp_f32_e32 v87, v87
	s_waitcnt lgkmcnt(1)
	v_mfma_f32_32x32x16_bf16 v[112:127], v[152:155], v[144:147], v[112:127]
	v_add_u32_e32 v240, v235, v217
	ds_read_b128 v[152:155], v203 offset:57344
	ds_read_b128 v[160:163], v240 offset:12288
	v_exp_f32_e32 v88, v88
	v_exp_f32_e32 v89, v89
	v_exp_f32_e32 v90, v90
	v_exp_f32_e32 v91, v91
	v_exp_f32_e32 v92, v92
	s_waitcnt lgkmcnt(2)
	v_mfma_f32_32x32x16_bf16 v[96:111], v[156:159], v[144:147], v[96:111]
	v_exp_f32_e32 v93, v93
	v_exp_f32_e32 v94, v94
	v_exp_f32_e32 v95, v95
	v_add_f32_e32 v168, v65, v64
	v_add_f32_e32 v168, v66, v168
	s_waitcnt lgkmcnt(1)
	v_mfma_f32_32x32x16_bf16 v[112:127], v[152:155], v[140:143], v[112:127]
	v_add_f32_e32 v152, v67, v168
	v_add_f32_e32 v152, v68, v152
	v_add_f32_e32 v152, v69, v152
	v_add_u32_e32 v241, v235, v223
	ds_read_b128 v[156:159], v214 offset:57344
	ds_read_b128 v[164:167], v241 offset:12288
	v_add_f32_e32 v152, v70, v152
	v_add_f32_e32 v168, v71, v152
	s_waitcnt lgkmcnt(2)
	v_mfma_f32_32x32x16_bf16 v[96:111], v[160:163], v[140:143], v[96:111]
	s_nop 0
	v_add_f32_e32 v168, v72, v168
	v_add_f32_e32 v168, v73, v168
	v_add_f32_e32 v168, v74, v168
	s_waitcnt lgkmcnt(1)
	v_mfma_f32_32x32x16_bf16 v[112:127], v[156:159], v[136:139], v[112:127]
	v_add_f32_e32 v156, v75, v168
	v_add_f32_e32 v156, v76, v156
	v_add_f32_e32 v156, v77, v156
	v_add_u32_e32 v242, v235, v225
	ds_read_b128 v[152:155], v202 offset:57344
	ds_read_b128 v[160:163], v242 offset:12288
	v_add_f32_e32 v156, v78, v156
	v_add_f32_e32 v168, v79, v156
	s_waitcnt lgkmcnt(2)
	v_mfma_f32_32x32x16_bf16 v[96:111], v[164:167], v[136:139], v[96:111]
	s_nop 0
	v_add_f32_e32 v168, v80, v168
	v_add_f32_e32 v168, v81, v168
	v_add_f32_e32 v168, v82, v168
	s_waitcnt lgkmcnt(1)
	v_mfma_f32_32x32x16_bf16 v[112:127], v[152:155], v[132:135], v[112:127]
	v_add_f32_e32 v152, v83, v168
	v_add_f32_e32 v152, v84, v152
	v_add_f32_e32 v152, v85, v152
	v_add_u32_e32 v243, v235, v226
	ds_read_b128 v[156:159], v201 offset:57344
	ds_read_b128 v[164:167], v243 offset:12288
	v_add_f32_e32 v152, v86, v152
	v_add_f32_e32 v152, v87, v152
	s_waitcnt lgkmcnt(2)
	v_mfma_f32_32x32x16_bf16 v[96:111], v[160:163], v[132:135], v[96:111]
	s_nop 0
	v_add_f32_e32 v152, v88, v152
	v_add_f32_e32 v152, v89, v152
	v_add_f32_e32 v152, v90, v152
	s_waitcnt lgkmcnt(1)
	v_mfma_f32_32x32x16_bf16 v[112:127], v[156:159], v[128:131], v[112:127]
	v_add_f32_e32 v152, v91, v152
	v_add_u32_e32 v244, v235, v227
	v_add_f32_e32 v152, v92, v152
	ds_read_b128 v[160:163], v244 offset:12288
	ds_read_b128 v[168:171], v198 offset:57344
	ds_read_b128 v[182:185], v188
	v_add_f32_e32 v152, v93, v152
	v_add_f32_e32 v152, v94, v152
	v_add_f32_e32 v152, v95, v152
	s_waitcnt lgkmcnt(3)
	v_mfma_f32_32x32x16_bf16 v[96:111], v[164:167], v[128:131], v[96:111]
	s_waitcnt lgkmcnt(0)
	v_mfma_f32_32x32x16_bf16 v[112:127], v[168:171], v[182:185], v[112:127]
	v_add_u32_e32 v245, v235, v228
	v_mov_b32_e32 v153, v152
	ds_read_b128 v[164:167], v245 offset:12288
	ds_read_b128 v[206:209], v192 offset:57344
	ds_read_b128 v[210:213], v188 offset:1024
	v_permlane32_swap_b32_e32 v152, v153
	v_add_f32_e32 v251, v152, v153
	v_cvt_pk_bf16_f32 v152, v64, v65
	v_mfma_f32_32x32x16_bf16 v[96:111], v[160:163], v[182:185], v[96:111]
	v_cvt_pk_bf16_f32 v153, v66, v67
	v_cvt_pk_bf16_f32 v154, v68, v69
	v_cvt_pk_bf16_f32 v155, v70, v71
	v_fmac_f32_e32 v251, v180, v250
	v_permlane32_swap_b32_e32 v152, v154
	v_permlane32_swap_b32_e32 v153, v155
	s_waitcnt lgkmcnt(0)
	v_mfma_f32_32x32x16_bf16 v[112:127], v[206:209], v[210:213], v[112:127]
	v_add_u32_e32 v246, v235, v229
	ds_read_b128 v[64:67], v246 offset:12288
	ds_read_b128 v[68:71], v194 offset:57344
	ds_read_b128 v[160:163], v188 offset:2048
	v_cvt_pk_bf16_f32 v156, v72, v73
	v_cvt_pk_bf16_f32 v157, v74, v75
	v_cvt_pk_bf16_f32 v158, v76, v77
	v_cvt_pk_bf16_f32 v159, v78, v79
	v_mfma_f32_32x32x16_bf16 v[96:111], v[164:167], v[210:213], v[96:111]
	v_permlane32_swap_b32_e32 v156, v158
	v_permlane32_swap_b32_e32 v157, v159
	s_waitcnt lgkmcnt(0)
	v_mfma_f32_32x32x16_bf16 v[112:127], v[68:71], v[160:163], v[112:127]
	v_add_u32_e32 v247, v235, v230
	ds_read_b128 v[72:75], v247 offset:12288
	ds_read_b128 v[76:79], v190 offset:57344
	ds_read_b128 v[164:167], v188 offset:3072
	v_cvt_pk_bf16_f32 v80, v80, v81
	v_cvt_pk_bf16_f32 v81, v82, v83
	v_cvt_pk_bf16_f32 v82, v84, v85
	v_cvt_pk_bf16_f32 v83, v86, v87
	v_mfma_f32_32x32x16_bf16 v[96:111], v[64:67], v[160:163], v[96:111]
	v_permlane32_swap_b32_e32 v80, v82
	v_permlane32_swap_b32_e32 v81, v83
	s_waitcnt lgkmcnt(0)
	v_mfma_f32_32x32x16_bf16 v[112:127], v[76:79], v[164:167], v[112:127]
	v_add_u32_e32 v248, v235, v231
	ds_read_b128 v[64:67], v248 offset:12288
	ds_read_b128 v[68:71], v193 offset:57344
	ds_read_b128 v[160:163], v188 offset:4096
	v_cvt_pk_bf16_f32 v84, v88, v89
	v_cvt_pk_bf16_f32 v85, v90, v91
	v_cvt_pk_bf16_f32 v86, v92, v93
	v_cvt_pk_bf16_f32 v87, v94, v95
	v_mfma_f32_32x32x16_bf16 v[96:111], v[72:75], v[164:167], v[96:111]
	v_permlane32_swap_b32_e32 v84, v86
	v_permlane32_swap_b32_e32 v85, v87
	s_waitcnt lgkmcnt(0)
; template <class CF> __device__ __forceinline__ void pv_sm(f32x16* o, int vb, bf16x8 pa0, bf16x8 pa1, bf16x8 pa2, bf16x8 pa3, f32x16& p0, f32x16& p1, float& m_reg, float& mn, float& alpha) {
;   constexpr float C = CF::SCALE * 1.4426950408889634f;
;   s16x4 f[8];
;   pv_reads<0>(vb, f);
;   float pmax = p0[0];
; #pragma unroll
;   for (int r = 1; r < 16; ++r) pmax = fmaxf(pmax, p0[r]);
;   asm volatile("" : "+v"(pmax));
;   pv_mfma4(o[0], f, pa0, pa1, pa2, pa3);
;   pv_reads<1>(vb, f);
; #pragma unroll
;   for (int r = 0; r < 16; ++r) pmax = fmaxf(pmax, p1[r]);
;   { auto rr = __builtin_amdgcn_permlane32_swap(__float_as_uint(pmax), __float_as_uint(pmax), false, false);
;     pmax = fmaxf(__uint_as_float(rr[0]), __uint_as_float(rr[1])); }
;   asm volatile("" : "+v"(pmax));
;   pv_mfma4(o[1], f, pa0, pa1, pa2, pa3);
;   pv_reads<2>(vb, f);
;   if (__builtin_expect(__all(pmax - m_reg <= THR / CF::SCALE), 1)) { mn = m_reg; alpha = 1.f; }
;   else { mn = fmaxf(m_reg, pmax); alpha = __builtin_amdgcn_exp2f((m_reg - mn) * C); m_reg = mn; }
;   const float mnC = -mn * C;
; #pragma unroll
;   for (int r = 0; r < 16; ++r) p0[r] = fmaf(p0[r], C, mnC);
; #pragma unroll
;   for (int r = 0; r < 16; ++r) p1[r] = fmaf(p1[r], C, mnC);
;   asm volatile("" : "+v"(p0), "+v"(p1));
;   pv_mfma4(o[2], f, pa0, pa1, pa2, pa3);
;   pv_reads<3>(vb, f);
; #pragma unroll
;   for (int r = 0; r < 16; ++r) p0[r] = __builtin_amdgcn_exp2f(p0[r]);
;   asm volatile("" : "+v"(p0));
;   pv_mfma4(o[3], f, pa0, pa1, pa2, pa3);
	v_mfma_f32_32x32x16_bf16 v[112:127], v[68:71], v[160:163], v[112:127]
	v_add_u32_e32 v249, v235, v232
	ds_read_b128 v[68:71], v249 offset:12288
	ds_read_b128 v[72:75], v191 offset:57344
	ds_read_b128 v[76:79], v188 offset:5120
	v_mfma_f32_32x32x16_bf16 v[96:111], v[64:67], v[160:163], v[96:111]
	s_waitcnt lgkmcnt(0)
	v_mfma_f32_32x32x16_bf16 v[112:127], v[72:75], v[76:79], v[112:127]
	v_mfma_f32_32x32x16_bf16 v[96:111], v[68:71], v[76:79], v[96:111]
	v_lshl_add_u64 v[180:181], v[178:179], 0, s[8:9]
	s_mov_b32 s0, 0x3f900000
	v_add_co_u32_e32 v64, vcc, s0, v180
	s_mov_b32 s0, 0x3f940000
	s_nop 0
	v_addc_co_u32_e32 v65, vcc, 0, v181, vcc
	v_add_co_u32_e32 v66, vcc, s0, v180
	v_lshl_add_u64 v[182:183], v[176:177], 0, s[8:9]
	s_nop 0
	v_addc_co_u32_e32 v67, vcc, 0, v181, vcc
	global_load_dwordx4 v[88:91], v[64:65], off offset:256
	global_load_dwordx4 v[92:95], v[66:67], off offset:256
	v_add_co_u32_e32 v64, vcc, s85, v182
	s_mov_b32 s0, 0x4f8f0000
	s_nop 0
	v_addc_co_u32_e32 v65, vcc, 0, v183, vcc
	v_add_co_u32_e32 v66, vcc, s0, v182
	v_lshl_add_u64 v[184:185], v[174:175], 0, s[8:9]
	s_nop 0
	v_addc_co_u32_e32 v67, vcc, 0, v183, vcc
	global_load_dwordx4 v[160:163], v[64:65], off
	global_load_dwordx4 v[164:167], v[66:67], off
	v_add_co_u32_e32 v64, vcc, s85, v184
	s_nop 1
	v_addc_co_u32_e32 v65, vcc, 0, v185, vcc
	global_load_dwordx4 v[168:171], v[64:65], off offset:256
	ds_read_b64_tr_b16 v[64:65], v187 offset:0
	ds_read_b64_tr_b16 v[66:67], v187 offset:0x800
	ds_read_b64_tr_b16 v[68:69], v187 offset:0x1000
	ds_read_b64_tr_b16 v[70:71], v187 offset:0x1800
	ds_read_b64_tr_b16 v[72:73], v187 offset:0x2000
	ds_read_b64_tr_b16 v[74:75], v187 offset:0x2800
	ds_read_b64_tr_b16 v[76:77], v187 offset:0x3000
	ds_read_b64_tr_b16 v[78:79], v187 offset:0x3800
	s_waitcnt lgkmcnt(6)
	v_mfma_f32_32x32x16_bf16 v[0:15], v[152:155], v[64:67], v[0:15]
	v_max_f32_e32 v206, v112, v113
	v_max3_f32 v206, v206, v114, v115
	v_max3_f32 v206, v206, v116, v117
	v_max3_f32 v206, v206, v118, v119
	v_max3_f32 v206, v206, v120, v121
	s_waitcnt lgkmcnt(4)
	v_mfma_f32_32x32x16_bf16 v[0:15], v[156:159], v[68:71], v[0:15]
	v_max3_f32 v206, v206, v122, v123
	v_max3_f32 v206, v206, v124, v125
	v_max3_f32 v206, v206, v126, v127
	ds_read_b64_tr_b16 v[64:65], v187 offset:0x200
	ds_read_b64_tr_b16 v[66:67], v187 offset:0xa00
	ds_read_b64_tr_b16 v[68:69], v187 offset:0x1200
	s_waitcnt lgkmcnt(5)
	v_mfma_f32_32x32x16_bf16 v[0:15], v[80:83], v[72:75], v[0:15]
	ds_read_b64_tr_b16 v[70:71], v187 offset:0x1a00
	ds_read_b64_tr_b16 v[72:73], v187 offset:0x2200
	ds_read_b64_tr_b16 v[74:75], v187 offset:0x2a00
	s_waitcnt lgkmcnt(6)
	v_mfma_f32_32x32x16_bf16 v[0:15], v[84:87], v[76:79], v[0:15]
	ds_read_b64_tr_b16 v[76:77], v187 offset:0x3200
	ds_read_b64_tr_b16 v[78:79], v187 offset:0x3a00
	s_waitcnt lgkmcnt(6)
	v_mfma_f32_32x32x16_bf16 v[48:63], v[152:155], v[64:67], v[48:63]
	v_max3_f32 v206, v206, v96, v97
	v_max3_f32 v206, v206, v98, v99
	v_max3_f32 v206, v206, v100, v101
	v_max3_f32 v206, v206, v102, v103
	v_max3_f32 v206, v206, v104, v105
	v_max3_f32 v206, v206, v106, v107
	v_max3_f32 v206, v206, v108, v109
	s_waitcnt lgkmcnt(4)
	v_mfma_f32_32x32x16_bf16 v[48:63], v[156:159], v[68:71], v[48:63]
	v_max3_f32 v206, v206, v110, v111
	v_mov_b32_e32 v207, v206
	s_nop 1
	v_permlane32_swap_b32_e32 v206, v207
	v_max_f32_e32 v218, v206, v207
	s_waitcnt lgkmcnt(2)
	v_mfma_f32_32x32x16_bf16 v[48:63], v[80:83], v[72:75], v[48:63]
	ds_read_b64_tr_b16 v[64:65], v187 offset:0x400
	ds_read_b64_tr_b16 v[66:67], v187 offset:0xc00
	ds_read_b64_tr_b16 v[68:69], v187 offset:0x1400
	ds_read_b64_tr_b16 v[70:71], v187 offset:0x1c00
	ds_read_b64_tr_b16 v[206:207], v187 offset:0x2400
	ds_read_b64_tr_b16 v[208:209], v187 offset:0x2c00
	s_waitcnt lgkmcnt(6)
	v_mfma_f32_32x32x16_bf16 v[48:63], v[84:87], v[76:79], v[48:63]
	ds_read_b64_tr_b16 v[210:211], v187 offset:0x3400
	ds_read_b64_tr_b16 v[212:213], v187 offset:0x3c00
	s_waitcnt lgkmcnt(6)
	v_mfma_f32_32x32x16_bf16 v[32:47], v[152:155], v[64:67], v[32:47]
	v_sub_f32_e32 v72, v218, v233
	v_cmp_ge_f32_e32 vcc, s63, v72
	v_max_f32_e32 v72, v233, v218
	v_sub_f32_e32 v73, v233, v72
	v_mul_f32_e32 v73, 0x3dd53b94, v73
	s_waitcnt lgkmcnt(4)
	v_mfma_f32_32x32x16_bf16 v[32:47], v[156:159], v[68:71], v[32:47]
	s_cmp_eq_u64 vcc, exec
	v_exp_f32_e32 v73, v73
	s_cselect_b64 vcc, -1, 0
	v_cndmask_b32_e32 v233, v72, v233, vcc
	v_mul_f32_e32 v218, 0xbdd53b94, v233
	v_cndmask_b32_e64 v252, v73, 1.0, vcc
	v_pk_fma_f32 v[78:79], v[126:127], s[84:85], v[218:219] op_sel_hi:[1,0,0]
	s_waitcnt lgkmcnt(2)
	v_mfma_f32_32x32x16_bf16 v[32:47], v[80:83], v[206:209], v[32:47]
	ds_read_b64_tr_b16 v[206:207], v187 offset:0x1600
	ds_read_b64_tr_b16 v[208:209], v187 offset:0x1e00
	v_fma_f32 v76, v124, s84, v218
	v_fma_f32 v77, v125, s84, v218
	v_fma_f32 v74, v122, s84, v218
	v_fma_f32 v75, v123, s84, v218
	v_fma_f32 v72, v120, s84, v218
	v_fma_f32 v73, v121, s84, v218
	v_pk_fma_f32 v[70:71], v[118:119], s[84:85], v[218:219] op_sel_hi:[1,0,0]
	v_pk_fma_f32 v[68:69], v[116:117], s[84:85], v[218:219] op_sel_hi:[1,0,0]
	v_pk_fma_f32 v[66:67], v[114:115], s[84:85], v[218:219] op_sel_hi:[1,0,0]
	v_pk_fma_f32 v[64:65], v[112:113], s[84:85], v[218:219] op_sel_hi:[1,0,0]
	v_pk_fma_f32 v[126:127], v[110:111], s[84:85], v[218:219] op_sel_hi:[1,0,0]
	v_pk_fma_f32 v[124:125], v[108:109], s[84:85], v[218:219] op_sel_hi:[1,0,0]
	v_pk_fma_f32 v[122:123], v[106:107], s[84:85], v[218:219] op_sel_hi:[1,0,0]
	v_pk_fma_f32 v[120:121], v[104:105], s[84:85], v[218:219] op_sel_hi:[1,0,0]
	v_pk_fma_f32 v[118:119], v[102:103], s[84:85], v[218:219] op_sel_hi:[1,0,0]
	v_pk_fma_f32 v[116:117], v[100:101], s[84:85], v[218:219] op_sel_hi:[1,0,0]
	v_pk_fma_f32 v[114:115], v[98:99], s[84:85], v[218:219] op_sel_hi:[1,0,0]
	v_pk_fma_f32 v[112:113], v[96:97], s[84:85], v[218:219] op_sel_hi:[1,0,0]
	ds_read_b64_tr_b16 v[104:105], v187 offset:0x600
	ds_read_b64_tr_b16 v[106:107], v187 offset:0xe00
	ds_read_b64_tr_b16 v[218:219], v187 offset:0x3600
	ds_read_b64_tr_b16 v[220:221], v187 offset:0x3e00
	s_waitcnt lgkmcnt(6)
	v_mfma_f32_32x32x16_bf16 v[32:47], v[84:87], v[210:213], v[32:47]
	s_waitcnt vmcnt(0)
	ds_write_b128 v197, v[160:163] offset:32768
	ds_write_b128 v197, v[164:167] offset:45056
	ds_write_b128 v199, v[168:171] offset:32768
	ds_read_b64_tr_b16 v[210:211], v187 offset:0x2600
	ds_read_b64_tr_b16 v[212:213], v187 offset:0x2e00
	s_waitcnt lgkmcnt(7)
	v_mfma_f32_32x32x16_bf16 v[16:31], v[152:155], v[104:107], v[16:31]
	s_waitcnt lgkmcnt(0)
	s_barrier
; #define ATT_SBAR() __builtin_amdgcn_sched_barrier(0)
; #define ATT_QRD(dst, g) do { _Pragma("unroll") for (int t = 0; t < 2; ++t) { const int cb = ((2 * (g) + t) * 16 + hi * 8) * 2; \
;     dst[2 * t] = *reinterpret_cast<const bf16x8*>(kr + (cb ^ sw)); dst[2 * t + 1] = *reinterpret_cast<const bf16x8*>(kr + 32 * CF::KPITCH + (cb ^ sw)); } } while (0)
; template <class CF> __device__ __forceinline__ void qk_sm1(f32x16& n0, f32x16& n1, const char* Ks, const bf16x8* qr, const char* qx, int r32, int hi, ...
;   static_assert(CF::ND0 == 12, "qk_sm1: 12 d0 steps");
;   n0 = f32x16{}; n1 = f32x16{};
;   const char* kr = Ks + r32 * CF::KPITCH; const int sw = (r32 & CF::KSWM) << 4;
;   bf16x8 kf[2][2], qf[2];
;     ...
;   ATT_QRD(0, 0); asm volatile("s_waitcnt lgkmcnt(0)" ::: "memory"); ATT_SBAR();
;   float ps = 0;
; #pragma unroll
;   for (int g = 0; g < 12; ++g) {
;     if (g + 1 < 12) ATT_QRD((g + 1) & 1, g + 1);
;     if (g < 2) {
; #pragma unroll
;       for (int r = 0; r < 8; ++r) p1[8 * g + r] = __builtin_amdgcn_exp2f(p1[8 * g + r]);
;       if (g == 1) asm volatile("" : "+v"(p1)); }
;     else if (g < 6) {
; #pragma unroll
;       for (int r = 0; r < 8; ++r) ps += (g < 4 ? p0[8 * (g - 2) + r] : p1[8 * (g - 4) + r]);
;       asm volatile("" : "+v"(ps)); }
;     else if (g == 6) {
;       { auto rr = __builtin_amdgcn_permlane32_swap(__float_as_uint(ps), __float_as_uint(ps), false, false);
;         ps = __uint_as_float(rr[0]) + __uint_as_float(rr[1]); }
;       l_reg = l_reg * alpha + ps;
;       ATT_PK4(p0, 0, pa0);
;       asm volatile("" : "+v"(l_reg), "+v"(pa0)); }
;     else if (g == 7) { ATT_PK4(p0, 8, pa1); asm volatile("" : "+v"(pa1)); }
;     else if (g == 8) { ATT_PK4(p1, 0, pa2); asm volatile("" : "+v"(pa2)); }
;     else if (g == 9) { ATT_PK4(p1, 8, pa3); asm volatile("" : "+v"(pa3)); }
;     ATT_QMM(g & 1, g);
;     if (g + 1 < 12) { asm volatile("s_waitcnt lgkmcnt(0)" ::: "memory"); ATT_SBAR(); }
;   }
; template <class CF> __device__ __forceinline__ void pv_sm(f32x16* o, int vb, bf16x8 pa0, bf16x8 pa1, bf16x8 pa2, bf16x8 pa3, f32x16& p0, f32x16& p1, float& m_reg, float& mn, float& alpha) {
;     ...
; #pragma unroll
;   for (int r = 0; r < 16; ++r) p0[r] = __builtin_amdgcn_exp2f(p0[r]);
;   asm volatile("" : "+v"(p0));
;   pv_mfma4(o[3], f, pa0, pa1, pa2, pa3);
	ds_write_b128 v195, v[88:91]
	v_exp_f32_e32 v96, v64
	v_exp_f32_e32 v97, v65
	v_exp_f32_e32 v98, v66
	v_exp_f32_e32 v99, v67
	v_exp_f32_e32 v100, v68
	v_exp_f32_e32 v101, v69
	v_exp_f32_e32 v102, v70
	v_mfma_f32_32x32x16_bf16 v[16:31], v[156:159], v[206:209], v[16:31]
	ds_write_b128 v196, v[92:95]
	v_exp_f32_e32 v103, v71
	v_exp_f32_e32 v104, v72
	v_exp_f32_e32 v105, v73
	v_exp_f32_e32 v106, v74
	v_exp_f32_e32 v107, v75
	v_exp_f32_e32 v108, v76
	v_exp_f32_e32 v109, v77
	v_mfma_f32_32x32x16_bf16 v[16:31], v[80:83], v[210:213], v[16:31]
	v_exp_f32_e32 v110, v78
	v_exp_f32_e32 v111, v79
	v_mfma_f32_32x32x16_bf16 v[16:31], v[84:87], v[218:221], v[16:31]
	v_cmp_gt_f32_e32 vcc, 1.0, v252
	s_cbranch_vccz .LBB0_1729
	s_and_saveexec_b64 s[12:13], s[4:5]
	ds_write_b32 v224, v252 offset:128
	s_or_b64 exec, exec, s[12:13]
	s_waitcnt lgkmcnt(0)
	v_add_u32_e32 v76, v186, v204
	ds_read_b128 v[64:67], v76 offset:224
	ds_read_b128 v[68:71], v76 offset:192
	ds_read_b128 v[72:75], v76 offset:160
	ds_read_b128 v[76:79], v76 offset:128
	s_waitcnt lgkmcnt(3)
	v_pk_mul_f32 v[12:13], v[12:13], v[64:65]
	s_waitcnt lgkmcnt(2)
	v_pk_mul_f32 v[8:9], v[8:9], v[68:69]
	s_waitcnt lgkmcnt(1)
	v_pk_mul_f32 v[4:5], v[4:5], v[72:73]
	v_pk_mul_f32 v[14:15], v[14:15], v[66:67]
	v_pk_mul_f32 v[10:11], v[10:11], v[70:71]
	v_pk_mul_f32 v[6:7], v[6:7], v[74:75]
	s_waitcnt lgkmcnt(0)
	v_pk_mul_f32 v[2:3], v[2:3], v[78:79]
	v_pk_mul_f32 v[0:1], v[0:1], v[76:77]
	v_pk_mul_f32 v[60:61], v[60:61], v[64:65]
	v_pk_mul_f32 v[56:57], v[56:57], v[68:69]
	v_pk_mul_f32 v[52:53], v[52:53], v[72:73]
	v_pk_mul_f32 v[62:63], v[62:63], v[66:67]
	v_pk_mul_f32 v[58:59], v[58:59], v[70:71]
	v_pk_mul_f32 v[54:55], v[54:55], v[74:75]
	v_pk_mul_f32 v[50:51], v[50:51], v[78:79]
	v_pk_mul_f32 v[48:49], v[48:49], v[76:77]
	v_pk_mul_f32 v[44:45], v[44:45], v[64:65]
	v_pk_mul_f32 v[40:41], v[40:41], v[68:69]
	v_pk_mul_f32 v[36:37], v[36:37], v[72:73]
	v_pk_mul_f32 v[46:47], v[46:47], v[66:67]
	v_pk_mul_f32 v[42:43], v[42:43], v[70:71]
	v_pk_mul_f32 v[38:39], v[38:39], v[74:75]
	v_pk_mul_f32 v[34:35], v[34:35], v[78:79]
	v_pk_mul_f32 v[32:33], v[32:33], v[76:77]
	v_pk_mul_f32 v[28:29], v[28:29], v[64:65]
	v_pk_mul_f32 v[24:25], v[24:25], v[68:69]
	v_pk_mul_f32 v[20:21], v[20:21], v[72:73]
	v_pk_mul_f32 v[30:31], v[30:31], v[66:67]
	v_pk_mul_f32 v[26:27], v[26:27], v[70:71]
	v_pk_mul_f32 v[22:23], v[22:23], v[74:75]
	v_pk_mul_f32 v[18:19], v[18:19], v[78:79]
	v_pk_mul_f32 v[16:17], v[16:17], v[76:77]
.LBB0_1729:
	ds_read_b128 v[64:67], v237 offset:32768
	ds_read_b128 v[68:71], v237 offset:45056
	s_waitcnt lgkmcnt(1)
	v_mfma_f32_32x32x16_bf16 v[80:95], v[64:67], v[148:151], 0
	ds_read_b128 v[152:155], v215 offset:32768
	ds_read_b128 v[156:159], v215 offset:45056
	v_exp_f32_e32 v112, v112
	v_exp_f32_e32 v113, v113
	v_exp_f32_e32 v114, v114
	v_exp_f32_e32 v115, v115
	v_exp_f32_e32 v116, v116
	s_waitcnt lgkmcnt(2)
	v_mfma_f32_32x32x16_bf16 v[64:79], v[68:71], v[148:151], 0
	v_exp_f32_e32 v117, v117
	v_exp_f32_e32 v118, v118
	v_exp_f32_e32 v119, v119
	s_waitcnt lgkmcnt(1)
	v_mfma_f32_32x32x16_bf16 v[80:95], v[152:155], v[144:147], v[80:95]
	ds_read_b128 v[152:155], v203 offset:32768
	ds_read_b128 v[160:163], v203 offset:45056
	v_exp_f32_e32 v120, v120
	v_exp_f32_e32 v121, v121
	v_exp_f32_e32 v122, v122
	v_exp_f32_e32 v123, v123
	v_exp_f32_e32 v124, v124
	v_exp_f32_e32 v125, v125
	s_waitcnt lgkmcnt(2)
	v_mfma_f32_32x32x16_bf16 v[64:79], v[156:159], v[144:147], v[64:79]
	v_exp_f32_e32 v126, v126
	v_exp_f32_e32 v127, v127
	v_add_f32_e32 v168, v97, v96
	v_add_f32_e32 v168, v98, v168
	s_waitcnt lgkmcnt(1)
	v_mfma_f32_32x32x16_bf16 v[80:95], v[152:155], v[140:143], v[80:95]
	v_add_f32_e32 v152, v99, v168
	v_add_f32_e32 v152, v100, v152
	v_add_f32_e32 v152, v101, v152
	ds_read_b128 v[156:159], v214 offset:32768
	ds_read_b128 v[164:167], v214 offset:45056
	v_add_f32_e32 v152, v102, v152
	v_add_f32_e32 v168, v103, v152
	s_waitcnt lgkmcnt(2)
	v_mfma_f32_32x32x16_bf16 v[64:79], v[160:163], v[140:143], v[64:79]
	v_add_f32_e32 v168, v104, v168
	v_add_f32_e32 v168, v105, v168
	v_add_f32_e32 v168, v106, v168
	s_waitcnt lgkmcnt(1)
	v_mfma_f32_32x32x16_bf16 v[80:95], v[156:159], v[136:139], v[80:95]
	v_add_f32_e32 v156, v107, v168
	v_add_f32_e32 v156, v108, v156
	v_add_f32_e32 v156, v109, v156
	ds_read_b128 v[152:155], v202 offset:32768
	ds_read_b128 v[160:163], v202 offset:45056
	v_add_f32_e32 v156, v110, v156
	v_add_f32_e32 v168, v111, v156
	s_waitcnt lgkmcnt(2)
	v_mfma_f32_32x32x16_bf16 v[64:79], v[164:167], v[136:139], v[64:79]
	v_add_f32_e32 v168, v112, v168
	v_add_f32_e32 v168, v113, v168
	v_add_f32_e32 v168, v114, v168
	s_waitcnt lgkmcnt(1)
	v_mfma_f32_32x32x16_bf16 v[80:95], v[152:155], v[132:135], v[80:95]
	v_add_f32_e32 v152, v115, v168
	v_add_f32_e32 v152, v116, v152
	v_add_f32_e32 v152, v117, v152
	ds_read_b128 v[156:159], v201 offset:32768
	ds_read_b128 v[164:167], v201 offset:45056
	v_add_f32_e32 v152, v118, v152
	v_add_f32_e32 v152, v119, v152
	s_waitcnt lgkmcnt(2)
	v_mfma_f32_32x32x16_bf16 v[64:79], v[160:163], v[132:135], v[64:79]
	v_add_f32_e32 v152, v120, v152
	v_add_f32_e32 v152, v121, v152
	v_add_f32_e32 v152, v122, v152
	s_waitcnt lgkmcnt(1)
	v_mfma_f32_32x32x16_bf16 v[80:95], v[156:159], v[128:131], v[80:95]
	v_add_f32_e32 v152, v123, v152
	v_add_f32_e32 v152, v124, v152
	ds_read_b128 v[160:163], v198 offset:45056
	ds_read_b128 v[168:171], v198 offset:32768
	ds_read_b128 v[206:209], v188
	v_add_f32_e32 v152, v125, v152
	v_add_f32_e32 v152, v126, v152
	v_add_f32_e32 v152, v127, v152
	s_waitcnt lgkmcnt(3)
	v_mfma_f32_32x32x16_bf16 v[64:79], v[164:167], v[128:131], v[64:79]
	s_waitcnt lgkmcnt(0)
; #define ATT_SBAR() __builtin_amdgcn_sched_barrier(0)
; #define ATT_QRD(dst, g) do { _Pragma("unroll") for (int t = 0; t < 2; ++t) { const int cb = ((2 * (g) + t) * 16 + hi * 8) * 2; \
;     dst[2 * t] = *reinterpret_cast<const bf16x8*>(kr + (cb ^ sw)); dst[2 * t + 1] = *reinterpret_cast<const bf16x8*>(kr + 32 * CF::KPITCH + (cb ^ sw)); } } while (0)
; template <class CF> __device__ __forceinline__ void qk_sm1(f32x16& n0, f32x16& n1, const char* Ks, const bf16x8* qr, const char* qx, int r32, int hi, ...
;     ...
;   ATT_QRD(0, 0); asm volatile("s_waitcnt lgkmcnt(0)" ::: "memory"); ATT_SBAR();
;   float ps = 0;
; #pragma unroll
;   for (int g = 0; g < 12; ++g) {
;     if (g + 1 < 12) ATT_QRD((g + 1) & 1, g + 1);
;     if (g < 2) {
; #pragma unroll
;       for (int r = 0; r < 8; ++r) p1[8 * g + r] = __builtin_amdgcn_exp2f(p1[8 * g + r]);
;       if (g == 1) asm volatile("" : "+v"(p1)); }
;     else if (g < 6) {
; #pragma unroll
;       for (int r = 0; r < 8; ++r) ps += (g < 4 ? p0[8 * (g - 2) + r] : p1[8 * (g - 4) + r]);
;       asm volatile("" : "+v"(ps)); }
;     else if (g == 6) {
;       { auto rr = __builtin_amdgcn_permlane32_swap(__float_as_uint(ps), __float_as_uint(ps), false, false);
;         ps = __uint_as_float(rr[0]) + __uint_as_float(rr[1]); }
;       l_reg = l_reg * alpha + ps;
;       ATT_PK4(p0, 0, pa0);
;       asm volatile("" : "+v"(l_reg), "+v"(pa0)); }
;     else if (g == 7) { ATT_PK4(p0, 8, pa1); asm volatile("" : "+v"(pa1)); }
;     else if (g == 8) { ATT_PK4(p1, 0, pa2); asm volatile("" : "+v"(pa2)); }
;     else if (g == 9) { ATT_PK4(p1, 8, pa3); asm volatile("" : "+v"(pa3)); }
;     ATT_QMM(g & 1, g);
;     if (g + 1 < 12) { asm volatile("s_waitcnt lgkmcnt(0)" ::: "memory"); ATT_SBAR(); }
;   }
;     ...
; }
; template <class CF> __device__ __forceinline__ void pv_sm(f32x16* o, int vb, bf16x8 pa0, bf16x8 pa1, bf16x8 pa2, bf16x8 pa3, f32x16& p0, f32x16& p1, float& m_reg, float& mn, float& alpha) {
;   constexpr float C = CF::SCALE * 1.4426950408889634f;
;   s16x4 f[8];
;   pv_reads<0>(vb, f);
;   float pmax = p0[0];
; #pragma unroll
;   for (int r = 1; r < 16; ++r) pmax = fmaxf(pmax, p0[r]);
;   asm volatile("" : "+v"(pmax));
;   pv_mfma4(o[0], f, pa0, pa1, pa2, pa3);
;   pv_reads<1>(vb, f);
; #pragma unroll
;   for (int r = 0; r < 16; ++r) pmax = fmaxf(pmax, p1[r]);
	v_mfma_f32_32x32x16_bf16 v[80:95], v[168:171], v[206:209], v[80:95]
	v_mov_b32_e32 v153, v152
	ds_read_b128 v[164:167], v192 offset:45056
	ds_read_b128 v[210:213], v192 offset:32768
	ds_read_b128 v[218:221], v188 offset:1024
	v_permlane32_swap_b32_e32 v152, v153
	v_add_f32_e32 v250, v152, v153
	v_cvt_pk_bf16_f32 v152, v96, v97
	v_cvt_pk_bf16_f32 v153, v98, v99
	v_mfma_f32_32x32x16_bf16 v[64:79], v[160:163], v[206:209], v[64:79]
	v_cvt_pk_bf16_f32 v154, v100, v101
	v_cvt_pk_bf16_f32 v155, v102, v103
	v_fmac_f32_e32 v250, v251, v252
	v_permlane32_swap_b32_e32 v152, v154
	v_permlane32_swap_b32_e32 v153, v155
	s_waitcnt lgkmcnt(0)
	v_mfma_f32_32x32x16_bf16 v[80:95], v[210:213], v[218:221], v[80:95]
	ds_read_b128 v[96:99], v194 offset:45056
	ds_read_b128 v[100:103], v194 offset:32768
	ds_read_b128 v[160:163], v188 offset:2048
	v_cvt_pk_bf16_f32 v156, v104, v105
	v_cvt_pk_bf16_f32 v157, v106, v107
	v_cvt_pk_bf16_f32 v158, v108, v109
	v_cvt_pk_bf16_f32 v159, v110, v111
	s_nop 0
	v_permlane32_swap_b32_e32 v156, v158
	v_mfma_f32_32x32x16_bf16 v[64:79], v[164:167], v[218:221], v[64:79]
	v_permlane32_swap_b32_e32 v157, v159
	s_waitcnt lgkmcnt(0)
	v_mfma_f32_32x32x16_bf16 v[80:95], v[100:103], v[160:163], v[80:95]
	ds_read_b128 v[104:107], v190 offset:45056
	ds_read_b128 v[108:111], v190 offset:32768
	ds_read_b128 v[164:167], v188 offset:3072
	v_cvt_pk_bf16_f32 v112, v112, v113
	v_cvt_pk_bf16_f32 v113, v114, v115
	v_cvt_pk_bf16_f32 v114, v116, v117
	v_cvt_pk_bf16_f32 v115, v118, v119
	s_nop 0
	v_permlane32_swap_b32_e32 v112, v114
	v_mfma_f32_32x32x16_bf16 v[64:79], v[96:99], v[160:163], v[64:79]
	v_permlane32_swap_b32_e32 v113, v115
	s_waitcnt lgkmcnt(0)
	v_mfma_f32_32x32x16_bf16 v[80:95], v[108:111], v[164:167], v[80:95]
	ds_read_b128 v[96:99], v193 offset:45056
	ds_read_b128 v[100:103], v193 offset:32768
	ds_read_b128 v[160:163], v188 offset:4096
	v_cvt_pk_bf16_f32 v116, v120, v121
	v_cvt_pk_bf16_f32 v117, v122, v123
	v_cvt_pk_bf16_f32 v118, v124, v125
	v_cvt_pk_bf16_f32 v119, v126, v127
	s_nop 0
	v_permlane32_swap_b32_e32 v116, v118
	v_mfma_f32_32x32x16_bf16 v[64:79], v[104:107], v[164:167], v[64:79]
	v_permlane32_swap_b32_e32 v117, v119
	s_waitcnt lgkmcnt(0)
	v_mfma_f32_32x32x16_bf16 v[80:95], v[100:103], v[160:163], v[80:95]
	ds_read_b128 v[100:103], v191 offset:45056
	ds_read_b128 v[104:107], v191 offset:32768
	ds_read_b128 v[108:111], v188 offset:5120
	v_mfma_f32_32x32x16_bf16 v[64:79], v[96:99], v[160:163], v[64:79]
	s_waitcnt lgkmcnt(0)
	v_mfma_f32_32x32x16_bf16 v[80:95], v[104:107], v[108:111], v[80:95]
	v_mfma_f32_32x32x16_bf16 v[64:79], v[100:103], v[108:111], v[64:79]
	s_mov_b32 s0, 0x3f980000
	v_add_co_u32_e32 v96, vcc, s0, v180
	s_mov_b32 s0, 0x3f9c0000
	s_nop 0
	v_addc_co_u32_e32 v97, vcc, 0, v181, vcc
	v_add_co_u32_e32 v98, vcc, s0, v180
	s_mov_b32 s0, 0x4f950000
	s_nop 0
	v_addc_co_u32_e32 v99, vcc, 0, v181, vcc
	global_load_dwordx4 v[120:123], v[96:97], off offset:256
	global_load_dwordx4 v[124:127], v[98:99], off offset:256
	v_add_co_u32_e32 v96, vcc, s61, v182
	s_nop 1
	v_addc_co_u32_e32 v97, vcc, 0, v183, vcc
	v_add_co_u32_e32 v98, vcc, s0, v182
	s_nop 1
	v_addc_co_u32_e32 v99, vcc, 0, v183, vcc
	global_load_dwordx4 v[160:163], v[96:97], off
	global_load_dwordx4 v[164:167], v[98:99], off
	v_add_co_u32_e32 v96, vcc, s61, v184
	s_nop 1
	v_addc_co_u32_e32 v97, vcc, 0, v185, vcc
	global_load_dwordx4 v[168:171], v[96:97], off offset:256
	ds_read_b64_tr_b16 v[96:97], v189 offset:0
	ds_read_b64_tr_b16 v[98:99], v189 offset:0x800
	ds_read_b64_tr_b16 v[100:101], v189 offset:0x1000
	ds_read_b64_tr_b16 v[102:103], v189 offset:0x1800
	ds_read_b64_tr_b16 v[104:105], v189 offset:0x2000
	ds_read_b64_tr_b16 v[106:107], v189 offset:0x2800
	ds_read_b64_tr_b16 v[108:109], v189 offset:0x3000
	ds_read_b64_tr_b16 v[110:111], v189 offset:0x3800
	s_waitcnt lgkmcnt(6)
	v_mfma_f32_32x32x16_bf16 v[0:15], v[152:155], v[96:99], v[0:15]
	v_max_f32_e32 v180, v80, v81
	v_max3_f32 v180, v180, v82, v83
	v_max3_f32 v180, v180, v84, v85
	v_max3_f32 v180, v180, v86, v87
	v_max3_f32 v180, v180, v88, v89
	s_waitcnt lgkmcnt(4)
	v_mfma_f32_32x32x16_bf16 v[0:15], v[156:159], v[100:103], v[0:15]
	v_max3_f32 v180, v180, v90, v91
	v_max3_f32 v180, v180, v92, v93
	v_max3_f32 v180, v180, v94, v95
	ds_read_b64_tr_b16 v[96:97], v189 offset:0x200
	ds_read_b64_tr_b16 v[98:99], v189 offset:0xa00
	ds_read_b64_tr_b16 v[100:101], v189 offset:0x1200
	s_waitcnt lgkmcnt(5)
	v_mfma_f32_32x32x16_bf16 v[0:15], v[112:115], v[104:107], v[0:15]
	ds_read_b64_tr_b16 v[102:103], v189 offset:0x1a00
	ds_read_b64_tr_b16 v[104:105], v189 offset:0x2200
	ds_read_b64_tr_b16 v[106:107], v189 offset:0x2a00
	s_waitcnt lgkmcnt(6)
; template <class CF> __device__ __forceinline__ void pv_sm(f32x16* o, int vb, bf16x8 pa0, bf16x8 pa1, bf16x8 pa2, bf16x8 pa3, f32x16& p0, f32x16& p1, float& m_reg, float& mn, float& alpha) {
;     ...
;   for (int r = 0; r < 16; ++r) pmax = fmaxf(pmax, p1[r]);
;   { auto rr = __builtin_amdgcn_permlane32_swap(__float_as_uint(pmax), __float_as_uint(pmax), false, false);
;     pmax = fmaxf(__uint_as_float(rr[0]), __uint_as_float(rr[1])); }
;   asm volatile("" : "+v"(pmax));
;   pv_mfma4(o[1], f, pa0, pa1, pa2, pa3);
;   pv_reads<2>(vb, f);
;   if (__builtin_expect(__all(pmax - m_reg <= THR / CF::SCALE), 1)) { mn = m_reg; alpha = 1.f; }
;   else { mn = fmaxf(m_reg, pmax); alpha = __builtin_amdgcn_exp2f((m_reg - mn) * C); m_reg = mn; }
;   const float mnC = -mn * C;
; #pragma unroll
;   for (int r = 0; r < 16; ++r) p0[r] = fmaf(p0[r], C, mnC);
; #pragma unroll
;   for (int r = 0; r < 16; ++r) p1[r] = fmaf(p1[r], C, mnC);
;   asm volatile("" : "+v"(p0), "+v"(p1));
;   pv_mfma4(o[2], f, pa0, pa1, pa2, pa3);
;   pv_reads<3>(vb, f);
; #pragma unroll
;   for (int r = 0; r < 16; ++r) p0[r] = __builtin_amdgcn_exp2f(p0[r]);
;   asm volatile("" : "+v"(p0));
;   pv_mfma4(o[3], f, pa0, pa1, pa2, pa3);
	v_mfma_f32_32x32x16_bf16 v[0:15], v[116:119], v[108:111], v[0:15]
	ds_read_b64_tr_b16 v[108:109], v189 offset:0x3200
	ds_read_b64_tr_b16 v[110:111], v189 offset:0x3a00
	s_waitcnt lgkmcnt(6)
	v_mfma_f32_32x32x16_bf16 v[48:63], v[152:155], v[96:99], v[48:63]
	v_max3_f32 v180, v180, v64, v65
	v_max3_f32 v180, v180, v66, v67
	v_max3_f32 v180, v180, v68, v69
	v_max3_f32 v180, v180, v70, v71
	v_max3_f32 v180, v180, v72, v73
	v_max3_f32 v180, v180, v74, v75
	v_max3_f32 v180, v180, v76, v77
	s_waitcnt lgkmcnt(4)
	v_mfma_f32_32x32x16_bf16 v[48:63], v[156:159], v[100:103], v[48:63]
	v_max3_f32 v180, v180, v78, v79
	v_mov_b32_e32 v181, v180
	s_nop 1
	v_permlane32_swap_b32_e32 v180, v181
	v_max_f32_e32 v180, v180, v181
	s_waitcnt lgkmcnt(2)
	v_mfma_f32_32x32x16_bf16 v[48:63], v[112:115], v[104:107], v[48:63]
	ds_read_b64_tr_b16 v[96:97], v189 offset:0x400
	ds_read_b64_tr_b16 v[98:99], v189 offset:0xc00
	ds_read_b64_tr_b16 v[100:101], v189 offset:0x1400
	ds_read_b64_tr_b16 v[102:103], v189 offset:0x1c00
	ds_read_b64_tr_b16 v[182:183], v189 offset:0x2400
	ds_read_b64_tr_b16 v[184:185], v189 offset:0x2c00
	s_waitcnt lgkmcnt(6)
	v_mfma_f32_32x32x16_bf16 v[48:63], v[116:119], v[108:111], v[48:63]
	ds_read_b64_tr_b16 v[206:207], v189 offset:0x3400
	ds_read_b64_tr_b16 v[208:209], v189 offset:0x3c00
	s_waitcnt lgkmcnt(6)
	v_mfma_f32_32x32x16_bf16 v[32:47], v[152:155], v[96:99], v[32:47]
	v_sub_f32_e32 v104, v180, v233
	v_cmp_ge_f32_e32 vcc, s63, v104
	v_max_f32_e32 v104, v233, v180
	v_sub_f32_e32 v105, v233, v104
	v_mul_f32_e32 v105, 0x3dd53b94, v105
	s_waitcnt lgkmcnt(4)
	v_mfma_f32_32x32x16_bf16 v[32:47], v[156:159], v[100:103], v[32:47]
	s_cmp_eq_u64 vcc, exec
	v_exp_f32_e32 v105, v105
	s_cselect_b64 vcc, -1, 0
	v_cndmask_b32_e32 v233, v104, v233, vcc
	v_mul_f32_e32 v210, 0xbdd53b94, v233
	v_cndmask_b32_e64 v180, v105, 1.0, vcc
	v_pk_fma_f32 v[110:111], v[94:95], s[84:85], v[210:211] op_sel_hi:[1,0,0]
	s_waitcnt lgkmcnt(2)
	v_mfma_f32_32x32x16_bf16 v[32:47], v[112:115], v[182:185], v[32:47]
	ds_read_b64_tr_b16 v[182:183], v189 offset:0x1600
	ds_read_b64_tr_b16 v[184:185], v189 offset:0x1e00
	v_fma_f32 v108, v92, s84, v210
	v_fma_f32 v109, v93, s84, v210
	v_fma_f32 v106, v90, s84, v210
	v_fma_f32 v107, v91, s84, v210
	v_fma_f32 v104, v88, s84, v210
	v_fma_f32 v105, v89, s84, v210
	v_pk_fma_f32 v[102:103], v[86:87], s[84:85], v[210:211] op_sel_hi:[1,0,0]
	v_pk_fma_f32 v[100:101], v[84:85], s[84:85], v[210:211] op_sel_hi:[1,0,0]
	v_pk_fma_f32 v[98:99], v[82:83], s[84:85], v[210:211] op_sel_hi:[1,0,0]
	v_pk_fma_f32 v[96:97], v[80:81], s[84:85], v[210:211] op_sel_hi:[1,0,0]
	v_pk_fma_f32 v[94:95], v[78:79], s[84:85], v[210:211] op_sel_hi:[1,0,0]
	v_pk_fma_f32 v[92:93], v[76:77], s[84:85], v[210:211] op_sel_hi:[1,0,0]
	v_pk_fma_f32 v[90:91], v[74:75], s[84:85], v[210:211] op_sel_hi:[1,0,0]
	v_pk_fma_f32 v[88:89], v[72:73], s[84:85], v[210:211] op_sel_hi:[1,0,0]
	v_pk_fma_f32 v[86:87], v[70:71], s[84:85], v[210:211] op_sel_hi:[1,0,0]
	v_pk_fma_f32 v[84:85], v[68:69], s[84:85], v[210:211] op_sel_hi:[1,0,0]
	v_pk_fma_f32 v[82:83], v[66:67], s[84:85], v[210:211] op_sel_hi:[1,0,0]
	v_pk_fma_f32 v[80:81], v[64:65], s[84:85], v[210:211] op_sel_hi:[1,0,0]
	ds_read_b64_tr_b16 v[72:73], v189 offset:0x600
	ds_read_b64_tr_b16 v[74:75], v189 offset:0xe00
	ds_read_b64_tr_b16 v[210:211], v189 offset:0x3600
	ds_read_b64_tr_b16 v[212:213], v189 offset:0x3e00
	s_waitcnt lgkmcnt(6)
	v_mfma_f32_32x32x16_bf16 v[32:47], v[116:119], v[206:209], v[32:47]
	s_waitcnt vmcnt(0)
	ds_write_b128 v197, v[160:163] offset:57344
	ds_write_b128 v234, v[164:167] offset:57344
	ds_write_b128 v199, v[168:171] offset:57344
	ds_read_b64_tr_b16 v[206:207], v189 offset:0x2600
	ds_read_b64_tr_b16 v[208:209], v189 offset:0x2e00
	s_waitcnt lgkmcnt(7)
	v_mfma_f32_32x32x16_bf16 v[16:31], v[152:155], v[72:75], v[16:31]
	s_waitcnt lgkmcnt(0)
	s_barrier
	ds_write_b128 v195, v[120:123] offset:16384
	v_exp_f32_e32 v64, v96
	v_exp_f32_e32 v65, v97
	v_exp_f32_e32 v66, v98
	v_exp_f32_e32 v67, v99
	v_exp_f32_e32 v68, v100
	v_exp_f32_e32 v69, v101
	v_exp_f32_e32 v70, v102
	v_mfma_f32_32x32x16_bf16 v[16:31], v[156:159], v[182:185], v[16:31]
	ds_write_b128 v196, v[124:127] offset:16384
	v_exp_f32_e32 v71, v103
	v_exp_f32_e32 v72, v104
	v_exp_f32_e32 v73, v105
	v_exp_f32_e32 v74, v106
	v_exp_f32_e32 v75, v107
	v_exp_f32_e32 v76, v108
	v_exp_f32_e32 v77, v109
	v_mfma_f32_32x32x16_bf16 v[16:31], v[112:115], v[206:209], v[16:31]
	v_exp_f32_e32 v78, v110
	v_exp_f32_e32 v79, v111
	v_mfma_f32_32x32x16_bf16 v[16:31], v[116:119], v[210:213], v[16:31]
	v_cmp_gt_f32_e32 vcc, 1.0, v180
	s_cbranch_vccz .LBB0_1724
	s_and_saveexec_b64 s[12:13], s[4:5]
	s_cbranch_execz .LBB0_1723
	ds_write_b32 v224, v180 offset:128
	s_branch .LBB0_1723
